# RWKV scanner rewritten: state in MFMA accumulator layout, rank-2 update via v_mfma_f32_32x32x2_f32 (exact f32), waves split by value rows so no cross-wave exchange
# speedup vs baseline: 1.0751x; 1.0504x over previous
; __device__ void scan_chain(PRef p, int l, int chain, ScanSm* sm) {
;     ...
;   if (wave < 2) {
;     const int kh = wave;
;     float S[32];
; #pragma unroll
;     for (int j = 0; j < 32; j++) S[j] = 0.f;
;     bf16* Y = p.HY + (size_t)d * NROWS * 512 + h * 64 + lane;
;     float yprev = 0.f;
;     int rowcur = b * TPB + (d ? 255 : 0), rowprev = rowcur;
;     const int rstep = d ? -1 : 1;
;     const int ko = 32 * kh + (lane & 15);
.LBB0_606:
	s_andn2_saveexec_b64 s[6:7], s[20:21]
	s_cbranch_execz .LBB0_564
	v_and_b32_e32 v0, 63, v196
	v_lshrrev_b32_e32 v1, 6, v196
	v_and_b32_e32 v2, 12, v0
	v_lshlrev_b32_e32 v2, 3, v2
	v_lshrrev_b32_e32 v4, 5, v0
	v_lshl_add_u32 v2, v4, 4, v2
	v_and_b32_e32 v5, 3, v0
	v_lshl_add_u32 v10, v5, 2, v2
	v_and_b32_e32 v6, 31, v0
	v_lshlrev_b32_e32 v7, 2, v6
	v_lshlrev_b32_e32 v8, 8, v4
	v_sub_u32_e32 v11, v7, v8
	v_add_u32_e32 v11, 0x300, v11
	v_lshl_add_u32 v12, v1, 7, v7
	v_add_u32_e32 v12, 0x500, v12
	v_lshl_add_u32 v13, v1, 5, v6
	s_lshl_b32 s0, s63, 6
	v_add_u32_e32 v13, s0, v13
	v_lshlrev_b32_e32 v13, 1, v13
	s_mul_i32 s0, s62, 0x2400000
	s_add_u32 s12, s86, s0
	s_addc_u32 s13, s87, 0
	s_cmp_eq_u32 s62, 0
	s_mov_b32 s20, 0xfffffc00
	s_cselect_b32 s20, 0x400, s20
	s_cselect_b32 s21, 0, -1
	s_cselect_b32 s0, 0, 0xff
	s_add_i32 s0, s28, s0
	s_lshl_b32 s0, s0, 10
	s_add_u32 s16, s12, s0
	s_addc_u32 s17, s13, 0
	v_mov_b32_e32 v32, 0
	v_mov_b32_e32 v33, 0
	v_mov_b32_e32 v34, 0
	v_mov_b32_e32 v35, 0
	v_mov_b32_e32 v36, 0
	v_mov_b32_e32 v37, 0
	v_mov_b32_e32 v38, 0
	v_mov_b32_e32 v39, 0
	v_mov_b32_e32 v40, 0
	v_mov_b32_e32 v41, 0
	v_mov_b32_e32 v42, 0
	v_mov_b32_e32 v43, 0
	v_mov_b32_e32 v44, 0
	v_mov_b32_e32 v45, 0
	v_mov_b32_e32 v46, 0
	v_mov_b32_e32 v47, 0
	v_mov_b32_e32 v48, 0
	v_mov_b32_e32 v49, 0
	v_mov_b32_e32 v50, 0
	v_mov_b32_e32 v51, 0
	v_mov_b32_e32 v52, 0
	v_mov_b32_e32 v53, 0
	v_mov_b32_e32 v54, 0
	v_mov_b32_e32 v55, 0
	v_mov_b32_e32 v56, 0
	v_mov_b32_e32 v57, 0
	v_mov_b32_e32 v58, 0
	v_mov_b32_e32 v59, 0
	v_mov_b32_e32 v60, 0
	v_mov_b32_e32 v61, 0
	v_mov_b32_e32 v62, 0
	v_mov_b32_e32 v63, 0
	s_mov_b32 s15, 0
.Lscan_chunk:
	s_and_b32 s22, s15, 1
	s_mulk_i32 s22, 0x6000
	v_add_u32_e32 v14, s22, v10
	v_add_u32_e32 v15, s22, v11
	v_add_u32_e32 v16, s22, v12
	s_cmp_lg_u32 s15, 16
	s_cbranch_scc1 .Lscan_rowok
	s_cmp_eq_u32 s62, 0
	s_cselect_b32 s0, 0, 0x7ff
	s_add_i32 s0, s28, s0
	s_addk_i32 s0, 0x100
	s_lshl_b32 s0, s0, 10
	s_add_u32 s16, s12, s0
	s_addc_u32 s17, s13, 0
.Lscan_rowok:
	s_waitcnt lgkmcnt(0)
	s_barrier
	ds_read_b32 v100, v14 offset:256
	ds_read_b32 v101, v14 offset:384
	ds_read_b32 v104, v15 offset:0
	ds_read_b32 v105, v15 offset:128
	ds_read_b32 v108, v16 offset:0
	ds_read_b32 v110, v14 offset:1024
	ds_read_b32 v111, v14 offset:1152
	s_waitcnt lgkmcnt(0)
	ds_read_b32 v102, v14 offset:1792
	ds_read_b32 v103, v14 offset:1920
	ds_read_b32 v106, v15 offset:1536
	ds_read_b32 v107, v15 offset:1664
	ds_read_b32 v109, v16 offset:1536
	ds_read_b32 v112, v14 offset:2560
	ds_read_b32 v113, v14 offset:2688
	v_mul_f32_dpp v120, v100, v32 row_newbcast:0 row_mask:0xf bank_mask:0xf
	v_mul_f32_dpp v121, v100, v33 row_newbcast:1 row_mask:0xf bank_mask:0xf
	v_fmac_f32_dpp v120, v100, v34 row_newbcast:2 row_mask:0xf bank_mask:0xf
	v_fmac_f32_dpp v121, v100, v35 row_newbcast:3 row_mask:0xf bank_mask:0xf
	v_fmac_f32_dpp v120, v100, v36 row_newbcast:4 row_mask:0xf bank_mask:0xf
	v_fmac_f32_dpp v121, v100, v37 row_newbcast:5 row_mask:0xf bank_mask:0xf
	v_fmac_f32_dpp v120, v100, v38 row_newbcast:6 row_mask:0xf bank_mask:0xf
	v_fmac_f32_dpp v121, v100, v39 row_newbcast:7 row_mask:0xf bank_mask:0xf
	v_fmac_f32_dpp v120, v100, v40 row_newbcast:8 row_mask:0xf bank_mask:0xf
	v_fmac_f32_dpp v121, v100, v41 row_newbcast:9 row_mask:0xf bank_mask:0xf
	v_fmac_f32_dpp v120, v100, v42 row_newbcast:10 row_mask:0xf bank_mask:0xf
	v_fmac_f32_dpp v121, v100, v43 row_newbcast:11 row_mask:0xf bank_mask:0xf
	v_fmac_f32_dpp v120, v100, v44 row_newbcast:12 row_mask:0xf bank_mask:0xf
	v_fmac_f32_dpp v121, v100, v45 row_newbcast:13 row_mask:0xf bank_mask:0xf
	v_fmac_f32_dpp v120, v100, v46 row_newbcast:14 row_mask:0xf bank_mask:0xf
	v_fmac_f32_dpp v121, v100, v47 row_newbcast:15 row_mask:0xf bank_mask:0xf
	v_mul_f32_dpp v122, v101, v48 row_newbcast:0 row_mask:0xf bank_mask:0xf
	v_mul_f32_dpp v123, v101, v49 row_newbcast:1 row_mask:0xf bank_mask:0xf
	v_fmac_f32_dpp v122, v101, v50 row_newbcast:2 row_mask:0xf bank_mask:0xf
	v_fmac_f32_dpp v123, v101, v51 row_newbcast:3 row_mask:0xf bank_mask:0xf
	v_fmac_f32_dpp v122, v101, v52 row_newbcast:4 row_mask:0xf bank_mask:0xf
	v_fmac_f32_dpp v123, v101, v53 row_newbcast:5 row_mask:0xf bank_mask:0xf
	v_fmac_f32_dpp v122, v101, v54 row_newbcast:6 row_mask:0xf bank_mask:0xf
	v_fmac_f32_dpp v123, v101, v55 row_newbcast:7 row_mask:0xf bank_mask:0xf
	v_fmac_f32_dpp v122, v101, v56 row_newbcast:8 row_mask:0xf bank_mask:0xf
	v_fmac_f32_dpp v123, v101, v57 row_newbcast:9 row_mask:0xf bank_mask:0xf
	v_fmac_f32_dpp v122, v101, v58 row_newbcast:10 row_mask:0xf bank_mask:0xf
	v_fmac_f32_dpp v123, v101, v59 row_newbcast:11 row_mask:0xf bank_mask:0xf
	v_fmac_f32_dpp v122, v101, v60 row_newbcast:12 row_mask:0xf bank_mask:0xf
	v_fmac_f32_dpp v123, v101, v61 row_newbcast:13 row_mask:0xf bank_mask:0xf
	v_fmac_f32_dpp v122, v101, v62 row_newbcast:14 row_mask:0xf bank_mask:0xf
	v_fmac_f32_dpp v123, v101, v63 row_newbcast:15 row_mask:0xf bank_mask:0xf
	v_add_f32_e32 v120, v120, v121
	v_add_f32_e32 v122, v122, v123
	v_add_f32_e32 v128, v120, v122
	s_nop 1
	v_permlane32_swap_b32 v129, v128
	s_mov_b32 exec_lo, 0
	v_add_f32_e64 v108, -v129, -v128
	s_mov_b32 exec_lo, -1
	s_nop 0
	v_mfma_f32_32x32x2_f32 v[64:79], v104, v108, v[32:47]
	s_nop 15
	v_mfma_f32_32x32x2_f32 v[80:95], v105, v108, v[48:63]
	s_nop 7
	s_waitcnt lgkmcnt(0)
	ds_read_b32 v100, v14 offset:3328
	ds_read_b32 v101, v14 offset:3456
	ds_read_b32 v104, v15 offset:3072
	ds_read_b32 v105, v15 offset:3200
	ds_read_b32 v108, v16 offset:3072
	ds_read_b32 v114, v14 offset:4096
	ds_read_b32 v115, v14 offset:4224
	v_mul_f32_dpp v120, v102, v64 row_newbcast:0 row_mask:0xf bank_mask:0xf
	v_mul_f32_dpp v121, v102, v65 row_newbcast:1 row_mask:0xf bank_mask:0xf
	v_fmac_f32_dpp v120, v102, v66 row_newbcast:2 row_mask:0xf bank_mask:0xf
	v_fmac_f32_dpp v121, v102, v67 row_newbcast:3 row_mask:0xf bank_mask:0xf
	v_fmac_f32_dpp v120, v102, v68 row_newbcast:4 row_mask:0xf bank_mask:0xf
	v_fmac_f32_dpp v121, v102, v69 row_newbcast:5 row_mask:0xf bank_mask:0xf
	v_fmac_f32_dpp v120, v102, v70 row_newbcast:6 row_mask:0xf bank_mask:0xf
	v_fmac_f32_dpp v121, v102, v71 row_newbcast:7 row_mask:0xf bank_mask:0xf
	v_fmac_f32_dpp v120, v102, v72 row_newbcast:8 row_mask:0xf bank_mask:0xf
	v_fmac_f32_dpp v121, v102, v73 row_newbcast:9 row_mask:0xf bank_mask:0xf
	v_fmac_f32_dpp v120, v102, v74 row_newbcast:10 row_mask:0xf bank_mask:0xf
	v_fmac_f32_dpp v121, v102, v75 row_newbcast:11 row_mask:0xf bank_mask:0xf
	v_fmac_f32_dpp v120, v102, v76 row_newbcast:12 row_mask:0xf bank_mask:0xf
	v_fmac_f32_dpp v121, v102, v77 row_newbcast:13 row_mask:0xf bank_mask:0xf
	v_fmac_f32_dpp v120, v102, v78 row_newbcast:14 row_mask:0xf bank_mask:0xf
	v_fmac_f32_dpp v121, v102, v79 row_newbcast:15 row_mask:0xf bank_mask:0xf
	v_mul_f32_dpp v122, v103, v80 row_newbcast:0 row_mask:0xf bank_mask:0xf
	v_mul_f32_dpp v123, v103, v81 row_newbcast:1 row_mask:0xf bank_mask:0xf
	v_fmac_f32_dpp v122, v103, v82 row_newbcast:2 row_mask:0xf bank_mask:0xf
	v_fmac_f32_dpp v123, v103, v83 row_newbcast:3 row_mask:0xf bank_mask:0xf
	v_fmac_f32_dpp v122, v103, v84 row_newbcast:4 row_mask:0xf bank_mask:0xf
	v_fmac_f32_dpp v123, v103, v85 row_newbcast:5 row_mask:0xf bank_mask:0xf
	v_fmac_f32_dpp v122, v103, v86 row_newbcast:6 row_mask:0xf bank_mask:0xf
	v_fmac_f32_dpp v123, v103, v87 row_newbcast:7 row_mask:0xf bank_mask:0xf
	v_fmac_f32_dpp v122, v103, v88 row_newbcast:8 row_mask:0xf bank_mask:0xf
	v_fmac_f32_dpp v123, v103, v89 row_newbcast:9 row_mask:0xf bank_mask:0xf
	v_fmac_f32_dpp v122, v103, v90 row_newbcast:10 row_mask:0xf bank_mask:0xf
	v_fmac_f32_dpp v123, v103, v91 row_newbcast:11 row_mask:0xf bank_mask:0xf
	v_fmac_f32_dpp v122, v103, v92 row_newbcast:12 row_mask:0xf bank_mask:0xf
	v_fmac_f32_dpp v123, v103, v93 row_newbcast:13 row_mask:0xf bank_mask:0xf
	v_fmac_f32_dpp v122, v103, v94 row_newbcast:14 row_mask:0xf bank_mask:0xf
	v_fmac_f32_dpp v123, v103, v95 row_newbcast:15 row_mask:0xf bank_mask:0xf
	v_add_f32_e32 v120, v120, v121
	v_add_f32_e32 v122, v122, v123
	v_add_f32_e32 v128, v120, v122
	s_nop 1
	v_permlane32_swap_b32 v129, v128
	s_mov_b32 exec_lo, 0
	v_add_f32_e64 v109, -v129, -v128
	s_mov_b32 exec_lo, -1
	s_nop 0
	v_mfma_f32_32x32x2_f32 v[32:47], v106, v109, v[64:79]
	v_mul_f32_dpp v124, v110, v64 row_newbcast:0 row_mask:0xf bank_mask:0xf
	v_mul_f32_dpp v125, v110, v65 row_newbcast:1 row_mask:0xf bank_mask:0xf
	v_fmac_f32_dpp v124, v110, v66 row_newbcast:2 row_mask:0xf bank_mask:0xf
	v_fmac_f32_dpp v125, v110, v67 row_newbcast:3 row_mask:0xf bank_mask:0xf
	v_fmac_f32_dpp v124, v110, v68 row_newbcast:4 row_mask:0xf bank_mask:0xf
	v_fmac_f32_dpp v125, v110, v69 row_newbcast:5 row_mask:0xf bank_mask:0xf
	v_fmac_f32_dpp v124, v110, v70 row_newbcast:6 row_mask:0xf bank_mask:0xf
	v_fmac_f32_dpp v125, v110, v71 row_newbcast:7 row_mask:0xf bank_mask:0xf
	v_fmac_f32_dpp v124, v110, v72 row_newbcast:8 row_mask:0xf bank_mask:0xf
	v_fmac_f32_dpp v125, v110, v73 row_newbcast:9 row_mask:0xf bank_mask:0xf
	v_fmac_f32_dpp v124, v110, v74 row_newbcast:10 row_mask:0xf bank_mask:0xf
	v_fmac_f32_dpp v125, v110, v75 row_newbcast:11 row_mask:0xf bank_mask:0xf
	v_fmac_f32_dpp v124, v110, v76 row_newbcast:12 row_mask:0xf bank_mask:0xf
	v_fmac_f32_dpp v125, v110, v77 row_newbcast:13 row_mask:0xf bank_mask:0xf
	v_fmac_f32_dpp v124, v110, v78 row_newbcast:14 row_mask:0xf bank_mask:0xf
	v_fmac_f32_dpp v125, v110, v79 row_newbcast:15 row_mask:0xf bank_mask:0xf
	v_mfma_f32_32x32x2_f32 v[48:63], v107, v109, v[80:95]
	v_mul_f32_dpp v126, v111, v80 row_newbcast:0 row_mask:0xf bank_mask:0xf
	v_mul_f32_dpp v127, v111, v81 row_newbcast:1 row_mask:0xf bank_mask:0xf
	v_fmac_f32_dpp v126, v111, v82 row_newbcast:2 row_mask:0xf bank_mask:0xf
	v_fmac_f32_dpp v127, v111, v83 row_newbcast:3 row_mask:0xf bank_mask:0xf
	v_fmac_f32_dpp v126, v111, v84 row_newbcast:4 row_mask:0xf bank_mask:0xf
	v_fmac_f32_dpp v127, v111, v85 row_newbcast:5 row_mask:0xf bank_mask:0xf
	v_fmac_f32_dpp v126, v111, v86 row_newbcast:6 row_mask:0xf bank_mask:0xf
	v_fmac_f32_dpp v127, v111, v87 row_newbcast:7 row_mask:0xf bank_mask:0xf
	v_fmac_f32_dpp v126, v111, v88 row_newbcast:8 row_mask:0xf bank_mask:0xf
	v_fmac_f32_dpp v127, v111, v89 row_newbcast:9 row_mask:0xf bank_mask:0xf
	v_fmac_f32_dpp v126, v111, v90 row_newbcast:10 row_mask:0xf bank_mask:0xf
	v_fmac_f32_dpp v127, v111, v91 row_newbcast:11 row_mask:0xf bank_mask:0xf
	v_fmac_f32_dpp v126, v111, v92 row_newbcast:12 row_mask:0xf bank_mask:0xf
	v_fmac_f32_dpp v127, v111, v93 row_newbcast:13 row_mask:0xf bank_mask:0xf
	v_fmac_f32_dpp v126, v111, v94 row_newbcast:14 row_mask:0xf bank_mask:0xf
	v_fmac_f32_dpp v127, v111, v95 row_newbcast:15 row_mask:0xf bank_mask:0xf
	v_add_f32_e32 v124, v124, v125
	v_add_f32_e32 v126, v126, v127
	v_add_f32_e32 v130, v124, v126
	s_nop 1
	v_permlane32_swap_b32 v131, v130
	s_mov_b32 exec_lo, 0
	v_add_f32_e32 v133, v131, v130
	v_cvt_pk_bf16_f32 v133, v133, v133
	global_store_short v13, v133, s[16:17]
	s_mov_b32 exec_lo, -1
	s_add_u32 s16, s16, s20
	s_addc_u32 s17, s17, s21
	s_waitcnt lgkmcnt(0)
	ds_read_b32 v102, v14 offset:4864
	ds_read_b32 v103, v14 offset:4992
	ds_read_b32 v106, v15 offset:4608
	ds_read_b32 v107, v15 offset:4736
	ds_read_b32 v109, v16 offset:4608
	ds_read_b32 v116, v14 offset:5632
	ds_read_b32 v117, v14 offset:5760
	v_mul_f32_dpp v120, v100, v32 row_newbcast:0 row_mask:0xf bank_mask:0xf
	v_mul_f32_dpp v121, v100, v33 row_newbcast:1 row_mask:0xf bank_mask:0xf
	v_fmac_f32_dpp v120, v100, v34 row_newbcast:2 row_mask:0xf bank_mask:0xf
	v_fmac_f32_dpp v121, v100, v35 row_newbcast:3 row_mask:0xf bank_mask:0xf
	v_fmac_f32_dpp v120, v100, v36 row_newbcast:4 row_mask:0xf bank_mask:0xf
	v_fmac_f32_dpp v121, v100, v37 row_newbcast:5 row_mask:0xf bank_mask:0xf
	v_fmac_f32_dpp v120, v100, v38 row_newbcast:6 row_mask:0xf bank_mask:0xf
	v_fmac_f32_dpp v121, v100, v39 row_newbcast:7 row_mask:0xf bank_mask:0xf
	v_fmac_f32_dpp v120, v100, v40 row_newbcast:8 row_mask:0xf bank_mask:0xf
	v_fmac_f32_dpp v121, v100, v41 row_newbcast:9 row_mask:0xf bank_mask:0xf
	v_fmac_f32_dpp v120, v100, v42 row_newbcast:10 row_mask:0xf bank_mask:0xf
	v_fmac_f32_dpp v121, v100, v43 row_newbcast:11 row_mask:0xf bank_mask:0xf
	v_fmac_f32_dpp v120, v100, v44 row_newbcast:12 row_mask:0xf bank_mask:0xf
	v_fmac_f32_dpp v121, v100, v45 row_newbcast:13 row_mask:0xf bank_mask:0xf
	v_fmac_f32_dpp v120, v100, v46 row_newbcast:14 row_mask:0xf bank_mask:0xf
	v_fmac_f32_dpp v121, v100, v47 row_newbcast:15 row_mask:0xf bank_mask:0xf
	v_mul_f32_dpp v122, v101, v48 row_newbcast:0 row_mask:0xf bank_mask:0xf
	v_mul_f32_dpp v123, v101, v49 row_newbcast:1 row_mask:0xf bank_mask:0xf
	v_fmac_f32_dpp v122, v101, v50 row_newbcast:2 row_mask:0xf bank_mask:0xf
	v_fmac_f32_dpp v123, v101, v51 row_newbcast:3 row_mask:0xf bank_mask:0xf
	v_fmac_f32_dpp v122, v101, v52 row_newbcast:4 row_mask:0xf bank_mask:0xf
	v_fmac_f32_dpp v123, v101, v53 row_newbcast:5 row_mask:0xf bank_mask:0xf
	v_fmac_f32_dpp v122, v101, v54 row_newbcast:6 row_mask:0xf bank_mask:0xf
	v_fmac_f32_dpp v123, v101, v55 row_newbcast:7 row_mask:0xf bank_mask:0xf
	v_fmac_f32_dpp v122, v101, v56 row_newbcast:8 row_mask:0xf bank_mask:0xf
	v_fmac_f32_dpp v123, v101, v57 row_newbcast:9 row_mask:0xf bank_mask:0xf
	v_fmac_f32_dpp v122, v101, v58 row_newbcast:10 row_mask:0xf bank_mask:0xf
	v_fmac_f32_dpp v123, v101, v59 row_newbcast:11 row_mask:0xf bank_mask:0xf
	v_fmac_f32_dpp v122, v101, v60 row_newbcast:12 row_mask:0xf bank_mask:0xf
	v_fmac_f32_dpp v123, v101, v61 row_newbcast:13 row_mask:0xf bank_mask:0xf
	v_fmac_f32_dpp v122, v101, v62 row_newbcast:14 row_mask:0xf bank_mask:0xf
	v_fmac_f32_dpp v123, v101, v63 row_newbcast:15 row_mask:0xf bank_mask:0xf
	v_add_f32_e32 v120, v120, v121
	v_add_f32_e32 v122, v122, v123
	v_add_f32_e32 v128, v120, v122
	s_nop 1
	v_permlane32_swap_b32 v129, v128
	s_mov_b32 exec_lo, 0
	v_add_f32_e64 v108, -v129, -v128
	s_mov_b32 exec_lo, -1
	s_nop 0
	v_mfma_f32_32x32x2_f32 v[64:79], v104, v108, v[32:47]
	v_mul_f32_dpp v124, v112, v32 row_newbcast:0 row_mask:0xf bank_mask:0xf
	v_mul_f32_dpp v125, v112, v33 row_newbcast:1 row_mask:0xf bank_mask:0xf
	v_fmac_f32_dpp v124, v112, v34 row_newbcast:2 row_mask:0xf bank_mask:0xf
	v_fmac_f32_dpp v125, v112, v35 row_newbcast:3 row_mask:0xf bank_mask:0xf
	v_fmac_f32_dpp v124, v112, v36 row_newbcast:4 row_mask:0xf bank_mask:0xf
	v_fmac_f32_dpp v125, v112, v37 row_newbcast:5 row_mask:0xf bank_mask:0xf
	v_fmac_f32_dpp v124, v112, v38 row_newbcast:6 row_mask:0xf bank_mask:0xf
	v_fmac_f32_dpp v125, v112, v39 row_newbcast:7 row_mask:0xf bank_mask:0xf
	v_fmac_f32_dpp v124, v112, v40 row_newbcast:8 row_mask:0xf bank_mask:0xf
	v_fmac_f32_dpp v125, v112, v41 row_newbcast:9 row_mask:0xf bank_mask:0xf
	v_fmac_f32_dpp v124, v112, v42 row_newbcast:10 row_mask:0xf bank_mask:0xf
	v_fmac_f32_dpp v125, v112, v43 row_newbcast:11 row_mask:0xf bank_mask:0xf
	v_fmac_f32_dpp v124, v112, v44 row_newbcast:12 row_mask:0xf bank_mask:0xf
	v_fmac_f32_dpp v125, v112, v45 row_newbcast:13 row_mask:0xf bank_mask:0xf
	v_fmac_f32_dpp v124, v112, v46 row_newbcast:14 row_mask:0xf bank_mask:0xf
	v_fmac_f32_dpp v125, v112, v47 row_newbcast:15 row_mask:0xf bank_mask:0xf
	v_mfma_f32_32x32x2_f32 v[80:95], v105, v108, v[48:63]
	v_mul_f32_dpp v126, v113, v48 row_newbcast:0 row_mask:0xf bank_mask:0xf
	v_mul_f32_dpp v127, v113, v49 row_newbcast:1 row_mask:0xf bank_mask:0xf
	v_fmac_f32_dpp v126, v113, v50 row_newbcast:2 row_mask:0xf bank_mask:0xf
	v_fmac_f32_dpp v127, v113, v51 row_newbcast:3 row_mask:0xf bank_mask:0xf
	v_fmac_f32_dpp v126, v113, v52 row_newbcast:4 row_mask:0xf bank_mask:0xf
	v_fmac_f32_dpp v127, v113, v53 row_newbcast:5 row_mask:0xf bank_mask:0xf
	v_fmac_f32_dpp v126, v113, v54 row_newbcast:6 row_mask:0xf bank_mask:0xf
	v_fmac_f32_dpp v127, v113, v55 row_newbcast:7 row_mask:0xf bank_mask:0xf
	v_fmac_f32_dpp v126, v113, v56 row_newbcast:8 row_mask:0xf bank_mask:0xf
	v_fmac_f32_dpp v127, v113, v57 row_newbcast:9 row_mask:0xf bank_mask:0xf
	v_fmac_f32_dpp v126, v113, v58 row_newbcast:10 row_mask:0xf bank_mask:0xf
	v_fmac_f32_dpp v127, v113, v59 row_newbcast:11 row_mask:0xf bank_mask:0xf
	v_fmac_f32_dpp v126, v113, v60 row_newbcast:12 row_mask:0xf bank_mask:0xf
	v_fmac_f32_dpp v127, v113, v61 row_newbcast:13 row_mask:0xf bank_mask:0xf
	v_fmac_f32_dpp v126, v113, v62 row_newbcast:14 row_mask:0xf bank_mask:0xf
	v_fmac_f32_dpp v127, v113, v63 row_newbcast:15 row_mask:0xf bank_mask:0xf
	v_add_f32_e32 v124, v124, v125
	v_add_f32_e32 v126, v126, v127
	v_add_f32_e32 v130, v124, v126
	s_nop 1
	v_permlane32_swap_b32 v131, v130
	s_mov_b32 exec_lo, 0
	v_add_f32_e32 v133, v131, v130
	v_cvt_pk_bf16_f32 v133, v133, v133
	global_store_short v13, v133, s[16:17]
	s_mov_b32 exec_lo, -1
	s_add_u32 s16, s16, s20
	s_addc_u32 s17, s17, s21
	s_waitcnt lgkmcnt(0)
	ds_read_b32 v100, v14 offset:6400
	ds_read_b32 v101, v14 offset:6528
	ds_read_b32 v104, v15 offset:6144
	ds_read_b32 v105, v15 offset:6272
	ds_read_b32 v108, v16 offset:6144
	ds_read_b32 v110, v14 offset:7168
	ds_read_b32 v111, v14 offset:7296
	v_mul_f32_dpp v120, v102, v64 row_newbcast:0 row_mask:0xf bank_mask:0xf
	v_mul_f32_dpp v121, v102, v65 row_newbcast:1 row_mask:0xf bank_mask:0xf
	v_fmac_f32_dpp v120, v102, v66 row_newbcast:2 row_mask:0xf bank_mask:0xf
	v_fmac_f32_dpp v121, v102, v67 row_newbcast:3 row_mask:0xf bank_mask:0xf
	v_fmac_f32_dpp v120, v102, v68 row_newbcast:4 row_mask:0xf bank_mask:0xf
	v_fmac_f32_dpp v121, v102, v69 row_newbcast:5 row_mask:0xf bank_mask:0xf
	v_fmac_f32_dpp v120, v102, v70 row_newbcast:6 row_mask:0xf bank_mask:0xf
	v_fmac_f32_dpp v121, v102, v71 row_newbcast:7 row_mask:0xf bank_mask:0xf
	v_fmac_f32_dpp v120, v102, v72 row_newbcast:8 row_mask:0xf bank_mask:0xf
	v_fmac_f32_dpp v121, v102, v73 row_newbcast:9 row_mask:0xf bank_mask:0xf
	v_fmac_f32_dpp v120, v102, v74 row_newbcast:10 row_mask:0xf bank_mask:0xf
	v_fmac_f32_dpp v121, v102, v75 row_newbcast:11 row_mask:0xf bank_mask:0xf
	v_fmac_f32_dpp v120, v102, v76 row_newbcast:12 row_mask:0xf bank_mask:0xf
	v_fmac_f32_dpp v121, v102, v77 row_newbcast:13 row_mask:0xf bank_mask:0xf
	v_fmac_f32_dpp v120, v102, v78 row_newbcast:14 row_mask:0xf bank_mask:0xf
	v_fmac_f32_dpp v121, v102, v79 row_newbcast:15 row_mask:0xf bank_mask:0xf
	v_mul_f32_dpp v122, v103, v80 row_newbcast:0 row_mask:0xf bank_mask:0xf
	v_mul_f32_dpp v123, v103, v81 row_newbcast:1 row_mask:0xf bank_mask:0xf
	v_fmac_f32_dpp v122, v103, v82 row_newbcast:2 row_mask:0xf bank_mask:0xf
	v_fmac_f32_dpp v123, v103, v83 row_newbcast:3 row_mask:0xf bank_mask:0xf
	v_fmac_f32_dpp v122, v103, v84 row_newbcast:4 row_mask:0xf bank_mask:0xf
	v_fmac_f32_dpp v123, v103, v85 row_newbcast:5 row_mask:0xf bank_mask:0xf
	v_fmac_f32_dpp v122, v103, v86 row_newbcast:6 row_mask:0xf bank_mask:0xf
	v_fmac_f32_dpp v123, v103, v87 row_newbcast:7 row_mask:0xf bank_mask:0xf
	v_fmac_f32_dpp v122, v103, v88 row_newbcast:8 row_mask:0xf bank_mask:0xf
	v_fmac_f32_dpp v123, v103, v89 row_newbcast:9 row_mask:0xf bank_mask:0xf
	v_fmac_f32_dpp v122, v103, v90 row_newbcast:10 row_mask:0xf bank_mask:0xf
	v_fmac_f32_dpp v123, v103, v91 row_newbcast:11 row_mask:0xf bank_mask:0xf
	v_fmac_f32_dpp v122, v103, v92 row_newbcast:12 row_mask:0xf bank_mask:0xf
	v_fmac_f32_dpp v123, v103, v93 row_newbcast:13 row_mask:0xf bank_mask:0xf
	v_fmac_f32_dpp v122, v103, v94 row_newbcast:14 row_mask:0xf bank_mask:0xf
	v_fmac_f32_dpp v123, v103, v95 row_newbcast:15 row_mask:0xf bank_mask:0xf
	v_add_f32_e32 v120, v120, v121
	v_add_f32_e32 v122, v122, v123
	v_add_f32_e32 v128, v120, v122
	s_nop 1
	v_permlane32_swap_b32 v129, v128
	s_mov_b32 exec_lo, 0
	v_add_f32_e64 v109, -v129, -v128
	s_mov_b32 exec_lo, -1
	s_nop 0
	v_mfma_f32_32x32x2_f32 v[32:47], v106, v109, v[64:79]
	v_mul_f32_dpp v124, v114, v64 row_newbcast:0 row_mask:0xf bank_mask:0xf
	v_mul_f32_dpp v125, v114, v65 row_newbcast:1 row_mask:0xf bank_mask:0xf
	v_fmac_f32_dpp v124, v114, v66 row_newbcast:2 row_mask:0xf bank_mask:0xf
	v_fmac_f32_dpp v125, v114, v67 row_newbcast:3 row_mask:0xf bank_mask:0xf
	v_fmac_f32_dpp v124, v114, v68 row_newbcast:4 row_mask:0xf bank_mask:0xf
	v_fmac_f32_dpp v125, v114, v69 row_newbcast:5 row_mask:0xf bank_mask:0xf
	v_fmac_f32_dpp v124, v114, v70 row_newbcast:6 row_mask:0xf bank_mask:0xf
	v_fmac_f32_dpp v125, v114, v71 row_newbcast:7 row_mask:0xf bank_mask:0xf
	v_fmac_f32_dpp v124, v114, v72 row_newbcast:8 row_mask:0xf bank_mask:0xf
	v_fmac_f32_dpp v125, v114, v73 row_newbcast:9 row_mask:0xf bank_mask:0xf
	v_fmac_f32_dpp v124, v114, v74 row_newbcast:10 row_mask:0xf bank_mask:0xf
	v_fmac_f32_dpp v125, v114, v75 row_newbcast:11 row_mask:0xf bank_mask:0xf
	v_fmac_f32_dpp v124, v114, v76 row_newbcast:12 row_mask:0xf bank_mask:0xf
	v_fmac_f32_dpp v125, v114, v77 row_newbcast:13 row_mask:0xf bank_mask:0xf
	v_fmac_f32_dpp v124, v114, v78 row_newbcast:14 row_mask:0xf bank_mask:0xf
	v_fmac_f32_dpp v125, v114, v79 row_newbcast:15 row_mask:0xf bank_mask:0xf
	v_mfma_f32_32x32x2_f32 v[48:63], v107, v109, v[80:95]
	v_mul_f32_dpp v126, v115, v80 row_newbcast:0 row_mask:0xf bank_mask:0xf
	v_mul_f32_dpp v127, v115, v81 row_newbcast:1 row_mask:0xf bank_mask:0xf
	v_fmac_f32_dpp v126, v115, v82 row_newbcast:2 row_mask:0xf bank_mask:0xf
	v_fmac_f32_dpp v127, v115, v83 row_newbcast:3 row_mask:0xf bank_mask:0xf
	v_fmac_f32_dpp v126, v115, v84 row_newbcast:4 row_mask:0xf bank_mask:0xf
	v_fmac_f32_dpp v127, v115, v85 row_newbcast:5 row_mask:0xf bank_mask:0xf
	v_fmac_f32_dpp v126, v115, v86 row_newbcast:6 row_mask:0xf bank_mask:0xf
	v_fmac_f32_dpp v127, v115, v87 row_newbcast:7 row_mask:0xf bank_mask:0xf
	v_fmac_f32_dpp v126, v115, v88 row_newbcast:8 row_mask:0xf bank_mask:0xf
	v_fmac_f32_dpp v127, v115, v89 row_newbcast:9 row_mask:0xf bank_mask:0xf
	v_fmac_f32_dpp v126, v115, v90 row_newbcast:10 row_mask:0xf bank_mask:0xf
	v_fmac_f32_dpp v127, v115, v91 row_newbcast:11 row_mask:0xf bank_mask:0xf
	v_fmac_f32_dpp v126, v115, v92 row_newbcast:12 row_mask:0xf bank_mask:0xf
	v_fmac_f32_dpp v127, v115, v93 row_newbcast:13 row_mask:0xf bank_mask:0xf
	v_fmac_f32_dpp v126, v115, v94 row_newbcast:14 row_mask:0xf bank_mask:0xf
	v_fmac_f32_dpp v127, v115, v95 row_newbcast:15 row_mask:0xf bank_mask:0xf
	v_add_f32_e32 v124, v124, v125
	v_add_f32_e32 v126, v126, v127
	v_add_f32_e32 v130, v124, v126
	s_nop 1
	v_permlane32_swap_b32 v131, v130
	s_mov_b32 exec_lo, 0
	v_add_f32_e32 v133, v131, v130
	v_cvt_pk_bf16_f32 v133, v133, v133
	global_store_short v13, v133, s[16:17]
	s_mov_b32 exec_lo, -1
	s_add_u32 s16, s16, s20
	s_addc_u32 s17, s17, s21
	s_waitcnt lgkmcnt(0)
	ds_read_b32 v102, v14 offset:7936
	ds_read_b32 v103, v14 offset:8064
	ds_read_b32 v106, v15 offset:7680
	ds_read_b32 v107, v15 offset:7808
	ds_read_b32 v109, v16 offset:7680
	ds_read_b32 v112, v14 offset:8704
	ds_read_b32 v113, v14 offset:8832
	v_mul_f32_dpp v120, v100, v32 row_newbcast:0 row_mask:0xf bank_mask:0xf
	v_mul_f32_dpp v121, v100, v33 row_newbcast:1 row_mask:0xf bank_mask:0xf
	v_fmac_f32_dpp v120, v100, v34 row_newbcast:2 row_mask:0xf bank_mask:0xf
	v_fmac_f32_dpp v121, v100, v35 row_newbcast:3 row_mask:0xf bank_mask:0xf
	v_fmac_f32_dpp v120, v100, v36 row_newbcast:4 row_mask:0xf bank_mask:0xf
	v_fmac_f32_dpp v121, v100, v37 row_newbcast:5 row_mask:0xf bank_mask:0xf
	v_fmac_f32_dpp v120, v100, v38 row_newbcast:6 row_mask:0xf bank_mask:0xf
	v_fmac_f32_dpp v121, v100, v39 row_newbcast:7 row_mask:0xf bank_mask:0xf
	v_fmac_f32_dpp v120, v100, v40 row_newbcast:8 row_mask:0xf bank_mask:0xf
	v_fmac_f32_dpp v121, v100, v41 row_newbcast:9 row_mask:0xf bank_mask:0xf
	v_fmac_f32_dpp v120, v100, v42 row_newbcast:10 row_mask:0xf bank_mask:0xf
	v_fmac_f32_dpp v121, v100, v43 row_newbcast:11 row_mask:0xf bank_mask:0xf
	v_fmac_f32_dpp v120, v100, v44 row_newbcast:12 row_mask:0xf bank_mask:0xf
	v_fmac_f32_dpp v121, v100, v45 row_newbcast:13 row_mask:0xf bank_mask:0xf
	v_fmac_f32_dpp v120, v100, v46 row_newbcast:14 row_mask:0xf bank_mask:0xf
	v_fmac_f32_dpp v121, v100, v47 row_newbcast:15 row_mask:0xf bank_mask:0xf
	v_mul_f32_dpp v122, v101, v48 row_newbcast:0 row_mask:0xf bank_mask:0xf
	v_mul_f32_dpp v123, v101, v49 row_newbcast:1 row_mask:0xf bank_mask:0xf
	v_fmac_f32_dpp v122, v101, v50 row_newbcast:2 row_mask:0xf bank_mask:0xf
	v_fmac_f32_dpp v123, v101, v51 row_newbcast:3 row_mask:0xf bank_mask:0xf
	v_fmac_f32_dpp v122, v101, v52 row_newbcast:4 row_mask:0xf bank_mask:0xf
	v_fmac_f32_dpp v123, v101, v53 row_newbcast:5 row_mask:0xf bank_mask:0xf
	v_fmac_f32_dpp v122, v101, v54 row_newbcast:6 row_mask:0xf bank_mask:0xf
	v_fmac_f32_dpp v123, v101, v55 row_newbcast:7 row_mask:0xf bank_mask:0xf
	v_fmac_f32_dpp v122, v101, v56 row_newbcast:8 row_mask:0xf bank_mask:0xf
	v_fmac_f32_dpp v123, v101, v57 row_newbcast:9 row_mask:0xf bank_mask:0xf
	v_fmac_f32_dpp v122, v101, v58 row_newbcast:10 row_mask:0xf bank_mask:0xf
	v_fmac_f32_dpp v123, v101, v59 row_newbcast:11 row_mask:0xf bank_mask:0xf
	v_fmac_f32_dpp v122, v101, v60 row_newbcast:12 row_mask:0xf bank_mask:0xf
	v_fmac_f32_dpp v123, v101, v61 row_newbcast:13 row_mask:0xf bank_mask:0xf
	v_fmac_f32_dpp v122, v101, v62 row_newbcast:14 row_mask:0xf bank_mask:0xf
	v_fmac_f32_dpp v123, v101, v63 row_newbcast:15 row_mask:0xf bank_mask:0xf
	v_add_f32_e32 v120, v120, v121
	v_add_f32_e32 v122, v122, v123
	v_add_f32_e32 v128, v120, v122
	s_nop 1
	v_permlane32_swap_b32 v129, v128
	s_mov_b32 exec_lo, 0
	v_add_f32_e64 v108, -v129, -v128
	s_mov_b32 exec_lo, -1
	s_nop 0
	v_mfma_f32_32x32x2_f32 v[64:79], v104, v108, v[32:47]
	v_mul_f32_dpp v124, v116, v32 row_newbcast:0 row_mask:0xf bank_mask:0xf
	v_mul_f32_dpp v125, v116, v33 row_newbcast:1 row_mask:0xf bank_mask:0xf
	v_fmac_f32_dpp v124, v116, v34 row_newbcast:2 row_mask:0xf bank_mask:0xf
	v_fmac_f32_dpp v125, v116, v35 row_newbcast:3 row_mask:0xf bank_mask:0xf
	v_fmac_f32_dpp v124, v116, v36 row_newbcast:4 row_mask:0xf bank_mask:0xf
	v_fmac_f32_dpp v125, v116, v37 row_newbcast:5 row_mask:0xf bank_mask:0xf
	v_fmac_f32_dpp v124, v116, v38 row_newbcast:6 row_mask:0xf bank_mask:0xf
	v_fmac_f32_dpp v125, v116, v39 row_newbcast:7 row_mask:0xf bank_mask:0xf
	v_fmac_f32_dpp v124, v116, v40 row_newbcast:8 row_mask:0xf bank_mask:0xf
	v_fmac_f32_dpp v125, v116, v41 row_newbcast:9 row_mask:0xf bank_mask:0xf
	v_fmac_f32_dpp v124, v116, v42 row_newbcast:10 row_mask:0xf bank_mask:0xf
	v_fmac_f32_dpp v125, v116, v43 row_newbcast:11 row_mask:0xf bank_mask:0xf
	v_fmac_f32_dpp v124, v116, v44 row_newbcast:12 row_mask:0xf bank_mask:0xf
	v_fmac_f32_dpp v125, v116, v45 row_newbcast:13 row_mask:0xf bank_mask:0xf
	v_fmac_f32_dpp v124, v116, v46 row_newbcast:14 row_mask:0xf bank_mask:0xf
	v_fmac_f32_dpp v125, v116, v47 row_newbcast:15 row_mask:0xf bank_mask:0xf
	v_mfma_f32_32x32x2_f32 v[80:95], v105, v108, v[48:63]
	v_mul_f32_dpp v126, v117, v48 row_newbcast:0 row_mask:0xf bank_mask:0xf
	v_mul_f32_dpp v127, v117, v49 row_newbcast:1 row_mask:0xf bank_mask:0xf
	v_fmac_f32_dpp v126, v117, v50 row_newbcast:2 row_mask:0xf bank_mask:0xf
	v_fmac_f32_dpp v127, v117, v51 row_newbcast:3 row_mask:0xf bank_mask:0xf
	v_fmac_f32_dpp v126, v117, v52 row_newbcast:4 row_mask:0xf bank_mask:0xf
	v_fmac_f32_dpp v127, v117, v53 row_newbcast:5 row_mask:0xf bank_mask:0xf
	v_fmac_f32_dpp v126, v117, v54 row_newbcast:6 row_mask:0xf bank_mask:0xf
	v_fmac_f32_dpp v127, v117, v55 row_newbcast:7 row_mask:0xf bank_mask:0xf
	v_fmac_f32_dpp v126, v117, v56 row_newbcast:8 row_mask:0xf bank_mask:0xf
	v_fmac_f32_dpp v127, v117, v57 row_newbcast:9 row_mask:0xf bank_mask:0xf
	v_fmac_f32_dpp v126, v117, v58 row_newbcast:10 row_mask:0xf bank_mask:0xf
	v_fmac_f32_dpp v127, v117, v59 row_newbcast:11 row_mask:0xf bank_mask:0xf
	v_fmac_f32_dpp v126, v117, v60 row_newbcast:12 row_mask:0xf bank_mask:0xf
	v_fmac_f32_dpp v127, v117, v61 row_newbcast:13 row_mask:0xf bank_mask:0xf
	v_fmac_f32_dpp v126, v117, v62 row_newbcast:14 row_mask:0xf bank_mask:0xf
	v_fmac_f32_dpp v127, v117, v63 row_newbcast:15 row_mask:0xf bank_mask:0xf
	v_add_f32_e32 v124, v124, v125
	v_add_f32_e32 v126, v126, v127
	v_add_f32_e32 v130, v124, v126
	s_nop 1
	v_permlane32_swap_b32 v131, v130
	s_mov_b32 exec_lo, 0
	v_add_f32_e32 v133, v131, v130
	v_cvt_pk_bf16_f32 v133, v133, v133
	global_store_short v13, v133, s[16:17]
	s_mov_b32 exec_lo, -1
	s_add_u32 s16, s16, s20
	s_addc_u32 s17, s17, s21
	s_waitcnt lgkmcnt(0)
	ds_read_b32 v100, v14 offset:9472
	ds_read_b32 v101, v14 offset:9600
	ds_read_b32 v104, v15 offset:9216
	ds_read_b32 v105, v15 offset:9344
	ds_read_b32 v108, v16 offset:9216
	ds_read_b32 v114, v14 offset:10240
	ds_read_b32 v115, v14 offset:10368
	v_mul_f32_dpp v120, v102, v64 row_newbcast:0 row_mask:0xf bank_mask:0xf
	v_mul_f32_dpp v121, v102, v65 row_newbcast:1 row_mask:0xf bank_mask:0xf
	v_fmac_f32_dpp v120, v102, v66 row_newbcast:2 row_mask:0xf bank_mask:0xf
	v_fmac_f32_dpp v121, v102, v67 row_newbcast:3 row_mask:0xf bank_mask:0xf
	v_fmac_f32_dpp v120, v102, v68 row_newbcast:4 row_mask:0xf bank_mask:0xf
	v_fmac_f32_dpp v121, v102, v69 row_newbcast:5 row_mask:0xf bank_mask:0xf
	v_fmac_f32_dpp v120, v102, v70 row_newbcast:6 row_mask:0xf bank_mask:0xf
	v_fmac_f32_dpp v121, v102, v71 row_newbcast:7 row_mask:0xf bank_mask:0xf
	v_fmac_f32_dpp v120, v102, v72 row_newbcast:8 row_mask:0xf bank_mask:0xf
	v_fmac_f32_dpp v121, v102, v73 row_newbcast:9 row_mask:0xf bank_mask:0xf
	v_fmac_f32_dpp v120, v102, v74 row_newbcast:10 row_mask:0xf bank_mask:0xf
	v_fmac_f32_dpp v121, v102, v75 row_newbcast:11 row_mask:0xf bank_mask:0xf
	v_fmac_f32_dpp v120, v102, v76 row_newbcast:12 row_mask:0xf bank_mask:0xf
	v_fmac_f32_dpp v121, v102, v77 row_newbcast:13 row_mask:0xf bank_mask:0xf
	v_fmac_f32_dpp v120, v102, v78 row_newbcast:14 row_mask:0xf bank_mask:0xf
	v_fmac_f32_dpp v121, v102, v79 row_newbcast:15 row_mask:0xf bank_mask:0xf
	v_mul_f32_dpp v122, v103, v80 row_newbcast:0 row_mask:0xf bank_mask:0xf
	v_mul_f32_dpp v123, v103, v81 row_newbcast:1 row_mask:0xf bank_mask:0xf
	v_fmac_f32_dpp v122, v103, v82 row_newbcast:2 row_mask:0xf bank_mask:0xf
	v_fmac_f32_dpp v123, v103, v83 row_newbcast:3 row_mask:0xf bank_mask:0xf
	v_fmac_f32_dpp v122, v103, v84 row_newbcast:4 row_mask:0xf bank_mask:0xf
	v_fmac_f32_dpp v123, v103, v85 row_newbcast:5 row_mask:0xf bank_mask:0xf
	v_fmac_f32_dpp v122, v103, v86 row_newbcast:6 row_mask:0xf bank_mask:0xf
	v_fmac_f32_dpp v123, v103, v87 row_newbcast:7 row_mask:0xf bank_mask:0xf
	v_fmac_f32_dpp v122, v103, v88 row_newbcast:8 row_mask:0xf bank_mask:0xf
	v_fmac_f32_dpp v123, v103, v89 row_newbcast:9 row_mask:0xf bank_mask:0xf
	v_fmac_f32_dpp v122, v103, v90 row_newbcast:10 row_mask:0xf bank_mask:0xf
	v_fmac_f32_dpp v123, v103, v91 row_newbcast:11 row_mask:0xf bank_mask:0xf
	v_fmac_f32_dpp v122, v103, v92 row_newbcast:12 row_mask:0xf bank_mask:0xf
	v_fmac_f32_dpp v123, v103, v93 row_newbcast:13 row_mask:0xf bank_mask:0xf
	v_fmac_f32_dpp v122, v103, v94 row_newbcast:14 row_mask:0xf bank_mask:0xf
	v_fmac_f32_dpp v123, v103, v95 row_newbcast:15 row_mask:0xf bank_mask:0xf
	v_add_f32_e32 v120, v120, v121
	v_add_f32_e32 v122, v122, v123
	v_add_f32_e32 v128, v120, v122
	s_nop 1
	v_permlane32_swap_b32 v129, v128
	s_mov_b32 exec_lo, 0
	v_add_f32_e64 v109, -v129, -v128
	s_mov_b32 exec_lo, -1
	s_nop 0
	v_mfma_f32_32x32x2_f32 v[32:47], v106, v109, v[64:79]
	v_mul_f32_dpp v124, v110, v64 row_newbcast:0 row_mask:0xf bank_mask:0xf
	v_mul_f32_dpp v125, v110, v65 row_newbcast:1 row_mask:0xf bank_mask:0xf
	v_fmac_f32_dpp v124, v110, v66 row_newbcast:2 row_mask:0xf bank_mask:0xf
	v_fmac_f32_dpp v125, v110, v67 row_newbcast:3 row_mask:0xf bank_mask:0xf
	v_fmac_f32_dpp v124, v110, v68 row_newbcast:4 row_mask:0xf bank_mask:0xf
	v_fmac_f32_dpp v125, v110, v69 row_newbcast:5 row_mask:0xf bank_mask:0xf
	v_fmac_f32_dpp v124, v110, v70 row_newbcast:6 row_mask:0xf bank_mask:0xf
	v_fmac_f32_dpp v125, v110, v71 row_newbcast:7 row_mask:0xf bank_mask:0xf
	v_fmac_f32_dpp v124, v110, v72 row_newbcast:8 row_mask:0xf bank_mask:0xf
	v_fmac_f32_dpp v125, v110, v73 row_newbcast:9 row_mask:0xf bank_mask:0xf
	v_fmac_f32_dpp v124, v110, v74 row_newbcast:10 row_mask:0xf bank_mask:0xf
	v_fmac_f32_dpp v125, v110, v75 row_newbcast:11 row_mask:0xf bank_mask:0xf
	v_fmac_f32_dpp v124, v110, v76 row_newbcast:12 row_mask:0xf bank_mask:0xf
	v_fmac_f32_dpp v125, v110, v77 row_newbcast:13 row_mask:0xf bank_mask:0xf
	v_fmac_f32_dpp v124, v110, v78 row_newbcast:14 row_mask:0xf bank_mask:0xf
	v_fmac_f32_dpp v125, v110, v79 row_newbcast:15 row_mask:0xf bank_mask:0xf
	v_mfma_f32_32x32x2_f32 v[48:63], v107, v109, v[80:95]
	v_mul_f32_dpp v126, v111, v80 row_newbcast:0 row_mask:0xf bank_mask:0xf
	v_mul_f32_dpp v127, v111, v81 row_newbcast:1 row_mask:0xf bank_mask:0xf
	v_fmac_f32_dpp v126, v111, v82 row_newbcast:2 row_mask:0xf bank_mask:0xf
	v_fmac_f32_dpp v127, v111, v83 row_newbcast:3 row_mask:0xf bank_mask:0xf
	v_fmac_f32_dpp v126, v111, v84 row_newbcast:4 row_mask:0xf bank_mask:0xf
	v_fmac_f32_dpp v127, v111, v85 row_newbcast:5 row_mask:0xf bank_mask:0xf
	v_fmac_f32_dpp v126, v111, v86 row_newbcast:6 row_mask:0xf bank_mask:0xf
	v_fmac_f32_dpp v127, v111, v87 row_newbcast:7 row_mask:0xf bank_mask:0xf
	v_fmac_f32_dpp v126, v111, v88 row_newbcast:8 row_mask:0xf bank_mask:0xf
	v_fmac_f32_dpp v127, v111, v89 row_newbcast:9 row_mask:0xf bank_mask:0xf
	v_fmac_f32_dpp v126, v111, v90 row_newbcast:10 row_mask:0xf bank_mask:0xf
	v_fmac_f32_dpp v127, v111, v91 row_newbcast:11 row_mask:0xf bank_mask:0xf
	v_fmac_f32_dpp v126, v111, v92 row_newbcast:12 row_mask:0xf bank_mask:0xf
	v_fmac_f32_dpp v127, v111, v93 row_newbcast:13 row_mask:0xf bank_mask:0xf
	v_fmac_f32_dpp v126, v111, v94 row_newbcast:14 row_mask:0xf bank_mask:0xf
	v_fmac_f32_dpp v127, v111, v95 row_newbcast:15 row_mask:0xf bank_mask:0xf
	v_add_f32_e32 v124, v124, v125
	v_add_f32_e32 v126, v126, v127
	v_add_f32_e32 v130, v124, v126
	s_nop 1
	v_permlane32_swap_b32 v131, v130
	s_mov_b32 exec_lo, 0
	v_add_f32_e32 v133, v131, v130
	v_cvt_pk_bf16_f32 v133, v133, v133
	global_store_short v13, v133, s[16:17]
	s_mov_b32 exec_lo, -1
	s_add_u32 s16, s16, s20
	s_addc_u32 s17, s17, s21
	s_waitcnt lgkmcnt(0)
	ds_read_b32 v102, v14 offset:11008
	ds_read_b32 v103, v14 offset:11136
	ds_read_b32 v106, v15 offset:10752
	ds_read_b32 v107, v15 offset:10880
	ds_read_b32 v109, v16 offset:10752
	ds_read_b32 v116, v14 offset:11776
	ds_read_b32 v117, v14 offset:11904
	ds_read_b32 v118, v14 offset:10752
	ds_read_b32 v119, v14 offset:10880
	v_mul_f32_dpp v120, v100, v32 row_newbcast:0 row_mask:0xf bank_mask:0xf
	v_mul_f32_dpp v121, v100, v33 row_newbcast:1 row_mask:0xf bank_mask:0xf
	v_fmac_f32_dpp v120, v100, v34 row_newbcast:2 row_mask:0xf bank_mask:0xf
	v_fmac_f32_dpp v121, v100, v35 row_newbcast:3 row_mask:0xf bank_mask:0xf
	v_fmac_f32_dpp v120, v100, v36 row_newbcast:4 row_mask:0xf bank_mask:0xf
	v_fmac_f32_dpp v121, v100, v37 row_newbcast:5 row_mask:0xf bank_mask:0xf
	v_fmac_f32_dpp v120, v100, v38 row_newbcast:6 row_mask:0xf bank_mask:0xf
	v_fmac_f32_dpp v121, v100, v39 row_newbcast:7 row_mask:0xf bank_mask:0xf
	v_fmac_f32_dpp v120, v100, v40 row_newbcast:8 row_mask:0xf bank_mask:0xf
	v_fmac_f32_dpp v121, v100, v41 row_newbcast:9 row_mask:0xf bank_mask:0xf
	v_fmac_f32_dpp v120, v100, v42 row_newbcast:10 row_mask:0xf bank_mask:0xf
	v_fmac_f32_dpp v121, v100, v43 row_newbcast:11 row_mask:0xf bank_mask:0xf
	v_fmac_f32_dpp v120, v100, v44 row_newbcast:12 row_mask:0xf bank_mask:0xf
	v_fmac_f32_dpp v121, v100, v45 row_newbcast:13 row_mask:0xf bank_mask:0xf
	v_fmac_f32_dpp v120, v100, v46 row_newbcast:14 row_mask:0xf bank_mask:0xf
	v_fmac_f32_dpp v121, v100, v47 row_newbcast:15 row_mask:0xf bank_mask:0xf
	v_mul_f32_dpp v122, v101, v48 row_newbcast:0 row_mask:0xf bank_mask:0xf
	v_mul_f32_dpp v123, v101, v49 row_newbcast:1 row_mask:0xf bank_mask:0xf
	v_fmac_f32_dpp v122, v101, v50 row_newbcast:2 row_mask:0xf bank_mask:0xf
	v_fmac_f32_dpp v123, v101, v51 row_newbcast:3 row_mask:0xf bank_mask:0xf
	v_fmac_f32_dpp v122, v101, v52 row_newbcast:4 row_mask:0xf bank_mask:0xf
	v_fmac_f32_dpp v123, v101, v53 row_newbcast:5 row_mask:0xf bank_mask:0xf
	v_fmac_f32_dpp v122, v101, v54 row_newbcast:6 row_mask:0xf bank_mask:0xf
	v_fmac_f32_dpp v123, v101, v55 row_newbcast:7 row_mask:0xf bank_mask:0xf
	v_fmac_f32_dpp v122, v101, v56 row_newbcast:8 row_mask:0xf bank_mask:0xf
	v_fmac_f32_dpp v123, v101, v57 row_newbcast:9 row_mask:0xf bank_mask:0xf
	v_fmac_f32_dpp v122, v101, v58 row_newbcast:10 row_mask:0xf bank_mask:0xf
	v_fmac_f32_dpp v123, v101, v59 row_newbcast:11 row_mask:0xf bank_mask:0xf
	v_fmac_f32_dpp v122, v101, v60 row_newbcast:12 row_mask:0xf bank_mask:0xf
	v_fmac_f32_dpp v123, v101, v61 row_newbcast:13 row_mask:0xf bank_mask:0xf
	v_fmac_f32_dpp v122, v101, v62 row_newbcast:14 row_mask:0xf bank_mask:0xf
	v_fmac_f32_dpp v123, v101, v63 row_newbcast:15 row_mask:0xf bank_mask:0xf
	v_add_f32_e32 v120, v120, v121
	v_add_f32_e32 v122, v122, v123
	v_add_f32_e32 v128, v120, v122
	s_nop 1
	v_permlane32_swap_b32 v129, v128
	s_mov_b32 exec_lo, 0
	v_add_f32_e64 v108, -v129, -v128
	s_mov_b32 exec_lo, -1
	s_nop 0
	v_mfma_f32_32x32x2_f32 v[64:79], v104, v108, v[32:47]
	v_mul_f32_dpp v124, v112, v32 row_newbcast:0 row_mask:0xf bank_mask:0xf
	v_mul_f32_dpp v125, v112, v33 row_newbcast:1 row_mask:0xf bank_mask:0xf
	v_fmac_f32_dpp v124, v112, v34 row_newbcast:2 row_mask:0xf bank_mask:0xf
	v_fmac_f32_dpp v125, v112, v35 row_newbcast:3 row_mask:0xf bank_mask:0xf
	v_fmac_f32_dpp v124, v112, v36 row_newbcast:4 row_mask:0xf bank_mask:0xf
	v_fmac_f32_dpp v125, v112, v37 row_newbcast:5 row_mask:0xf bank_mask:0xf
	v_fmac_f32_dpp v124, v112, v38 row_newbcast:6 row_mask:0xf bank_mask:0xf
	v_fmac_f32_dpp v125, v112, v39 row_newbcast:7 row_mask:0xf bank_mask:0xf
	v_fmac_f32_dpp v124, v112, v40 row_newbcast:8 row_mask:0xf bank_mask:0xf
	v_fmac_f32_dpp v125, v112, v41 row_newbcast:9 row_mask:0xf bank_mask:0xf
	v_fmac_f32_dpp v124, v112, v42 row_newbcast:10 row_mask:0xf bank_mask:0xf
	v_fmac_f32_dpp v125, v112, v43 row_newbcast:11 row_mask:0xf bank_mask:0xf
	v_fmac_f32_dpp v124, v112, v44 row_newbcast:12 row_mask:0xf bank_mask:0xf
	v_fmac_f32_dpp v125, v112, v45 row_newbcast:13 row_mask:0xf bank_mask:0xf
	v_fmac_f32_dpp v124, v112, v46 row_newbcast:14 row_mask:0xf bank_mask:0xf
	v_fmac_f32_dpp v125, v112, v47 row_newbcast:15 row_mask:0xf bank_mask:0xf
	v_mfma_f32_32x32x2_f32 v[80:95], v105, v108, v[48:63]
	v_mul_f32_dpp v126, v113, v48 row_newbcast:0 row_mask:0xf bank_mask:0xf
	v_mul_f32_dpp v127, v113, v49 row_newbcast:1 row_mask:0xf bank_mask:0xf
	v_fmac_f32_dpp v126, v113, v50 row_newbcast:2 row_mask:0xf bank_mask:0xf
	v_fmac_f32_dpp v127, v113, v51 row_newbcast:3 row_mask:0xf bank_mask:0xf
	v_fmac_f32_dpp v126, v113, v52 row_newbcast:4 row_mask:0xf bank_mask:0xf
	v_fmac_f32_dpp v127, v113, v53 row_newbcast:5 row_mask:0xf bank_mask:0xf
	v_fmac_f32_dpp v126, v113, v54 row_newbcast:6 row_mask:0xf bank_mask:0xf
	v_fmac_f32_dpp v127, v113, v55 row_newbcast:7 row_mask:0xf bank_mask:0xf
	v_fmac_f32_dpp v126, v113, v56 row_newbcast:8 row_mask:0xf bank_mask:0xf
	v_fmac_f32_dpp v127, v113, v57 row_newbcast:9 row_mask:0xf bank_mask:0xf
	v_fmac_f32_dpp v126, v113, v58 row_newbcast:10 row_mask:0xf bank_mask:0xf
	v_fmac_f32_dpp v127, v113, v59 row_newbcast:11 row_mask:0xf bank_mask:0xf
	v_fmac_f32_dpp v126, v113, v60 row_newbcast:12 row_mask:0xf bank_mask:0xf
	v_fmac_f32_dpp v127, v113, v61 row_newbcast:13 row_mask:0xf bank_mask:0xf
	v_fmac_f32_dpp v126, v113, v62 row_newbcast:14 row_mask:0xf bank_mask:0xf
	v_fmac_f32_dpp v127, v113, v63 row_newbcast:15 row_mask:0xf bank_mask:0xf
	v_add_f32_e32 v124, v124, v125
	v_add_f32_e32 v126, v126, v127
	v_add_f32_e32 v130, v124, v126
	s_nop 1
	v_permlane32_swap_b32 v131, v130
	s_mov_b32 exec_lo, 0
	v_add_f32_e32 v133, v131, v130
	v_cvt_pk_bf16_f32 v133, v133, v133
	global_store_short v13, v133, s[16:17]
	s_mov_b32 exec_lo, -1
	s_add_u32 s16, s16, s20
	s_addc_u32 s17, s17, s21
	s_waitcnt lgkmcnt(0)
	ds_read_b32 v100, v14 offset:12544
	ds_read_b32 v101, v14 offset:12672
	ds_read_b32 v104, v15 offset:12288
	ds_read_b32 v105, v15 offset:12416
	ds_read_b32 v108, v16 offset:12288
	ds_read_b32 v110, v14 offset:13312
	ds_read_b32 v111, v14 offset:13440
	v_mul_f32_dpp v120, v102, v64 row_newbcast:0 row_mask:0xf bank_mask:0xf
	v_mul_f32_dpp v121, v102, v65 row_newbcast:1 row_mask:0xf bank_mask:0xf
	v_fmac_f32_dpp v120, v102, v66 row_newbcast:2 row_mask:0xf bank_mask:0xf
	v_fmac_f32_dpp v121, v102, v67 row_newbcast:3 row_mask:0xf bank_mask:0xf
	v_fmac_f32_dpp v120, v102, v68 row_newbcast:4 row_mask:0xf bank_mask:0xf
	v_fmac_f32_dpp v121, v102, v69 row_newbcast:5 row_mask:0xf bank_mask:0xf
	v_fmac_f32_dpp v120, v102, v70 row_newbcast:6 row_mask:0xf bank_mask:0xf
	v_fmac_f32_dpp v121, v102, v71 row_newbcast:7 row_mask:0xf bank_mask:0xf
	v_fmac_f32_dpp v120, v102, v72 row_newbcast:8 row_mask:0xf bank_mask:0xf
	v_fmac_f32_dpp v121, v102, v73 row_newbcast:9 row_mask:0xf bank_mask:0xf
	v_fmac_f32_dpp v120, v102, v74 row_newbcast:10 row_mask:0xf bank_mask:0xf
	v_fmac_f32_dpp v121, v102, v75 row_newbcast:11 row_mask:0xf bank_mask:0xf
	v_fmac_f32_dpp v120, v102, v76 row_newbcast:12 row_mask:0xf bank_mask:0xf
	v_fmac_f32_dpp v121, v102, v77 row_newbcast:13 row_mask:0xf bank_mask:0xf
	v_fmac_f32_dpp v120, v102, v78 row_newbcast:14 row_mask:0xf bank_mask:0xf
	v_fmac_f32_dpp v121, v102, v79 row_newbcast:15 row_mask:0xf bank_mask:0xf
	v_mul_f32_dpp v122, v103, v80 row_newbcast:0 row_mask:0xf bank_mask:0xf
	v_mul_f32_dpp v123, v103, v81 row_newbcast:1 row_mask:0xf bank_mask:0xf
	v_fmac_f32_dpp v122, v103, v82 row_newbcast:2 row_mask:0xf bank_mask:0xf
	v_fmac_f32_dpp v123, v103, v83 row_newbcast:3 row_mask:0xf bank_mask:0xf
	v_fmac_f32_dpp v122, v103, v84 row_newbcast:4 row_mask:0xf bank_mask:0xf
	v_fmac_f32_dpp v123, v103, v85 row_newbcast:5 row_mask:0xf bank_mask:0xf
	v_fmac_f32_dpp v122, v103, v86 row_newbcast:6 row_mask:0xf bank_mask:0xf
	v_fmac_f32_dpp v123, v103, v87 row_newbcast:7 row_mask:0xf bank_mask:0xf
	v_fmac_f32_dpp v122, v103, v88 row_newbcast:8 row_mask:0xf bank_mask:0xf
	v_fmac_f32_dpp v123, v103, v89 row_newbcast:9 row_mask:0xf bank_mask:0xf
	v_fmac_f32_dpp v122, v103, v90 row_newbcast:10 row_mask:0xf bank_mask:0xf
	v_fmac_f32_dpp v123, v103, v91 row_newbcast:11 row_mask:0xf bank_mask:0xf
	v_fmac_f32_dpp v122, v103, v92 row_newbcast:12 row_mask:0xf bank_mask:0xf
	v_fmac_f32_dpp v123, v103, v93 row_newbcast:13 row_mask:0xf bank_mask:0xf
	v_fmac_f32_dpp v122, v103, v94 row_newbcast:14 row_mask:0xf bank_mask:0xf
	v_fmac_f32_dpp v123, v103, v95 row_newbcast:15 row_mask:0xf bank_mask:0xf
	v_add_f32_e32 v120, v120, v121
	v_add_f32_e32 v122, v122, v123
	v_add_f32_e32 v128, v120, v122
	s_nop 1
	v_permlane32_swap_b32 v129, v128
	s_mov_b32 exec_lo, 0
	v_add_f32_e64 v109, -v129, -v128
	s_mov_b32 exec_lo, -1
	s_nop 0
	v_mfma_f32_32x32x2_f32 v[32:47], v106, v109, v[64:79]
	v_mul_f32_dpp v124, v114, v64 row_newbcast:0 row_mask:0xf bank_mask:0xf
	v_mul_f32_dpp v125, v114, v65 row_newbcast:1 row_mask:0xf bank_mask:0xf
	v_fmac_f32_dpp v124, v114, v66 row_newbcast:2 row_mask:0xf bank_mask:0xf
	v_fmac_f32_dpp v125, v114, v67 row_newbcast:3 row_mask:0xf bank_mask:0xf
	v_fmac_f32_dpp v124, v114, v68 row_newbcast:4 row_mask:0xf bank_mask:0xf
	v_fmac_f32_dpp v125, v114, v69 row_newbcast:5 row_mask:0xf bank_mask:0xf
	v_fmac_f32_dpp v124, v114, v70 row_newbcast:6 row_mask:0xf bank_mask:0xf
	v_fmac_f32_dpp v125, v114, v71 row_newbcast:7 row_mask:0xf bank_mask:0xf
	v_fmac_f32_dpp v124, v114, v72 row_newbcast:8 row_mask:0xf bank_mask:0xf
	v_fmac_f32_dpp v125, v114, v73 row_newbcast:9 row_mask:0xf bank_mask:0xf
	v_fmac_f32_dpp v124, v114, v74 row_newbcast:10 row_mask:0xf bank_mask:0xf
	v_fmac_f32_dpp v125, v114, v75 row_newbcast:11 row_mask:0xf bank_mask:0xf
	v_fmac_f32_dpp v124, v114, v76 row_newbcast:12 row_mask:0xf bank_mask:0xf
	v_fmac_f32_dpp v125, v114, v77 row_newbcast:13 row_mask:0xf bank_mask:0xf
	v_fmac_f32_dpp v124, v114, v78 row_newbcast:14 row_mask:0xf bank_mask:0xf
	v_fmac_f32_dpp v125, v114, v79 row_newbcast:15 row_mask:0xf bank_mask:0xf
	v_mfma_f32_32x32x2_f32 v[48:63], v107, v109, v[80:95]
	v_mul_f32_dpp v126, v115, v80 row_newbcast:0 row_mask:0xf bank_mask:0xf
	v_mul_f32_dpp v127, v115, v81 row_newbcast:1 row_mask:0xf bank_mask:0xf
	v_fmac_f32_dpp v126, v115, v82 row_newbcast:2 row_mask:0xf bank_mask:0xf
	v_fmac_f32_dpp v127, v115, v83 row_newbcast:3 row_mask:0xf bank_mask:0xf
	v_fmac_f32_dpp v126, v115, v84 row_newbcast:4 row_mask:0xf bank_mask:0xf
	v_fmac_f32_dpp v127, v115, v85 row_newbcast:5 row_mask:0xf bank_mask:0xf
	v_fmac_f32_dpp v126, v115, v86 row_newbcast:6 row_mask:0xf bank_mask:0xf
	v_fmac_f32_dpp v127, v115, v87 row_newbcast:7 row_mask:0xf bank_mask:0xf
	v_fmac_f32_dpp v126, v115, v88 row_newbcast:8 row_mask:0xf bank_mask:0xf
	v_fmac_f32_dpp v127, v115, v89 row_newbcast:9 row_mask:0xf bank_mask:0xf
	v_fmac_f32_dpp v126, v115, v90 row_newbcast:10 row_mask:0xf bank_mask:0xf
	v_fmac_f32_dpp v127, v115, v91 row_newbcast:11 row_mask:0xf bank_mask:0xf
	v_fmac_f32_dpp v126, v115, v92 row_newbcast:12 row_mask:0xf bank_mask:0xf
	v_fmac_f32_dpp v127, v115, v93 row_newbcast:13 row_mask:0xf bank_mask:0xf
	v_fmac_f32_dpp v126, v115, v94 row_newbcast:14 row_mask:0xf bank_mask:0xf
	v_fmac_f32_dpp v127, v115, v95 row_newbcast:15 row_mask:0xf bank_mask:0xf
	v_add_f32_e32 v124, v124, v125
	v_add_f32_e32 v126, v126, v127
	v_add_f32_e32 v130, v124, v126
	s_nop 1
	v_permlane32_swap_b32 v131, v130
	s_mov_b32 exec_lo, 0
	v_add_f32_e32 v133, v131, v130
	v_cvt_pk_bf16_f32 v133, v133, v133
	global_store_short v13, v133, s[16:17]
	s_mov_b32 exec_lo, -1
	s_add_u32 s16, s16, s20
	s_addc_u32 s17, s17, s21
	v_mul_f32_dpp v124, v116, v32 row_newbcast:0 row_mask:0xf bank_mask:0xf
	v_mul_f32_dpp v125, v116, v33 row_newbcast:1 row_mask:0xf bank_mask:0xf
	v_fmac_f32_dpp v124, v116, v34 row_newbcast:2 row_mask:0xf bank_mask:0xf
	v_fmac_f32_dpp v125, v116, v35 row_newbcast:3 row_mask:0xf bank_mask:0xf
	v_fmac_f32_dpp v124, v116, v36 row_newbcast:4 row_mask:0xf bank_mask:0xf
	v_fmac_f32_dpp v125, v116, v37 row_newbcast:5 row_mask:0xf bank_mask:0xf
	v_fmac_f32_dpp v124, v116, v38 row_newbcast:6 row_mask:0xf bank_mask:0xf
	v_fmac_f32_dpp v125, v116, v39 row_newbcast:7 row_mask:0xf bank_mask:0xf
	v_fmac_f32_dpp v124, v116, v40 row_newbcast:8 row_mask:0xf bank_mask:0xf
	v_fmac_f32_dpp v125, v116, v41 row_newbcast:9 row_mask:0xf bank_mask:0xf
	v_fmac_f32_dpp v124, v116, v42 row_newbcast:10 row_mask:0xf bank_mask:0xf
	v_fmac_f32_dpp v125, v116, v43 row_newbcast:11 row_mask:0xf bank_mask:0xf
	v_fmac_f32_dpp v124, v116, v44 row_newbcast:12 row_mask:0xf bank_mask:0xf
	v_fmac_f32_dpp v125, v116, v45 row_newbcast:13 row_mask:0xf bank_mask:0xf
	v_fmac_f32_dpp v124, v116, v46 row_newbcast:14 row_mask:0xf bank_mask:0xf
	v_fmac_f32_dpp v125, v116, v47 row_newbcast:15 row_mask:0xf bank_mask:0xf
	v_mul_f32_dpp v126, v117, v48 row_newbcast:0 row_mask:0xf bank_mask:0xf
	v_mul_f32_dpp v127, v117, v49 row_newbcast:1 row_mask:0xf bank_mask:0xf
	v_fmac_f32_dpp v126, v117, v50 row_newbcast:2 row_mask:0xf bank_mask:0xf
	v_fmac_f32_dpp v127, v117, v51 row_newbcast:3 row_mask:0xf bank_mask:0xf
	v_fmac_f32_dpp v126, v117, v52 row_newbcast:4 row_mask:0xf bank_mask:0xf
	v_fmac_f32_dpp v127, v117, v53 row_newbcast:5 row_mask:0xf bank_mask:0xf
	v_fmac_f32_dpp v126, v117, v54 row_newbcast:6 row_mask:0xf bank_mask:0xf
	v_fmac_f32_dpp v127, v117, v55 row_newbcast:7 row_mask:0xf bank_mask:0xf
	v_fmac_f32_dpp v126, v117, v56 row_newbcast:8 row_mask:0xf bank_mask:0xf
	v_fmac_f32_dpp v127, v117, v57 row_newbcast:9 row_mask:0xf bank_mask:0xf
	v_fmac_f32_dpp v126, v117, v58 row_newbcast:10 row_mask:0xf bank_mask:0xf
	v_fmac_f32_dpp v127, v117, v59 row_newbcast:11 row_mask:0xf bank_mask:0xf
	v_fmac_f32_dpp v126, v117, v60 row_newbcast:12 row_mask:0xf bank_mask:0xf
	v_fmac_f32_dpp v127, v117, v61 row_newbcast:13 row_mask:0xf bank_mask:0xf
	v_fmac_f32_dpp v126, v117, v62 row_newbcast:14 row_mask:0xf bank_mask:0xf
	v_fmac_f32_dpp v127, v117, v63 row_newbcast:15 row_mask:0xf bank_mask:0xf
	v_add_f32_e32 v124, v124, v125
	v_add_f32_e32 v126, v126, v127
	v_add_f32_e32 v130, v124, v126
	s_nop 1
	v_permlane32_swap_b32 v131, v130
	s_mov_b32 exec_lo, 0
	v_add_f32_e32 v133, v131, v130
	v_cvt_pk_bf16_f32 v133, v133, v133
	global_store_short v13, v133, s[16:17]
	s_mov_b32 exec_lo, -1
	s_add_u32 s16, s16, s20
	s_addc_u32 s17, s17, s21
	v_mul_f32_dpp v32, v118, v32 row_newbcast:0 row_mask:0xf bank_mask:0xf
	v_mul_f32_dpp v33, v118, v33 row_newbcast:1 row_mask:0xf bank_mask:0xf
	v_mul_f32_dpp v34, v118, v34 row_newbcast:2 row_mask:0xf bank_mask:0xf
	v_mul_f32_dpp v35, v118, v35 row_newbcast:3 row_mask:0xf bank_mask:0xf
	v_mul_f32_dpp v36, v118, v36 row_newbcast:4 row_mask:0xf bank_mask:0xf
	v_mul_f32_dpp v37, v118, v37 row_newbcast:5 row_mask:0xf bank_mask:0xf
	v_mul_f32_dpp v38, v118, v38 row_newbcast:6 row_mask:0xf bank_mask:0xf
	v_mul_f32_dpp v39, v118, v39 row_newbcast:7 row_mask:0xf bank_mask:0xf
	v_mul_f32_dpp v40, v118, v40 row_newbcast:8 row_mask:0xf bank_mask:0xf
	v_mul_f32_dpp v41, v118, v41 row_newbcast:9 row_mask:0xf bank_mask:0xf
	v_mul_f32_dpp v42, v118, v42 row_newbcast:10 row_mask:0xf bank_mask:0xf
	v_mul_f32_dpp v43, v118, v43 row_newbcast:11 row_mask:0xf bank_mask:0xf
	v_mul_f32_dpp v44, v118, v44 row_newbcast:12 row_mask:0xf bank_mask:0xf
	v_mul_f32_dpp v45, v118, v45 row_newbcast:13 row_mask:0xf bank_mask:0xf
	v_mul_f32_dpp v46, v118, v46 row_newbcast:14 row_mask:0xf bank_mask:0xf
	v_mul_f32_dpp v47, v118, v47 row_newbcast:15 row_mask:0xf bank_mask:0xf
	v_mul_f32_dpp v48, v119, v48 row_newbcast:0 row_mask:0xf bank_mask:0xf
	v_mul_f32_dpp v49, v119, v49 row_newbcast:1 row_mask:0xf bank_mask:0xf
	v_mul_f32_dpp v50, v119, v50 row_newbcast:2 row_mask:0xf bank_mask:0xf
	v_mul_f32_dpp v51, v119, v51 row_newbcast:3 row_mask:0xf bank_mask:0xf
	v_mul_f32_dpp v52, v119, v52 row_newbcast:4 row_mask:0xf bank_mask:0xf
	v_mul_f32_dpp v53, v119, v53 row_newbcast:5 row_mask:0xf bank_mask:0xf
	v_mul_f32_dpp v54, v119, v54 row_newbcast:6 row_mask:0xf bank_mask:0xf
	v_mul_f32_dpp v55, v119, v55 row_newbcast:7 row_mask:0xf bank_mask:0xf
	v_mul_f32_dpp v56, v119, v56 row_newbcast:8 row_mask:0xf bank_mask:0xf
	v_mul_f32_dpp v57, v119, v57 row_newbcast:9 row_mask:0xf bank_mask:0xf
	v_mul_f32_dpp v58, v119, v58 row_newbcast:10 row_mask:0xf bank_mask:0xf
	v_mul_f32_dpp v59, v119, v59 row_newbcast:11 row_mask:0xf bank_mask:0xf
	v_mul_f32_dpp v60, v119, v60 row_newbcast:12 row_mask:0xf bank_mask:0xf
	v_mul_f32_dpp v61, v119, v61 row_newbcast:13 row_mask:0xf bank_mask:0xf
	v_mul_f32_dpp v62, v119, v62 row_newbcast:14 row_mask:0xf bank_mask:0xf
	v_mul_f32_dpp v63, v119, v63 row_newbcast:15 row_mask:0xf bank_mask:0xf
	s_waitcnt lgkmcnt(0)
	ds_read_b32 v102, v14 offset:14080
	ds_read_b32 v103, v14 offset:14208
	ds_read_b32 v106, v15 offset:13824
	ds_read_b32 v107, v15 offset:13952
	ds_read_b32 v109, v16 offset:13824
	ds_read_b32 v112, v14 offset:14848
	ds_read_b32 v113, v14 offset:14976
	v_mul_f32_dpp v120, v100, v32 row_newbcast:0 row_mask:0xf bank_mask:0xf
	v_mul_f32_dpp v121, v100, v33 row_newbcast:1 row_mask:0xf bank_mask:0xf
	v_fmac_f32_dpp v120, v100, v34 row_newbcast:2 row_mask:0xf bank_mask:0xf
	v_fmac_f32_dpp v121, v100, v35 row_newbcast:3 row_mask:0xf bank_mask:0xf
	v_fmac_f32_dpp v120, v100, v36 row_newbcast:4 row_mask:0xf bank_mask:0xf
	v_fmac_f32_dpp v121, v100, v37 row_newbcast:5 row_mask:0xf bank_mask:0xf
	v_fmac_f32_dpp v120, v100, v38 row_newbcast:6 row_mask:0xf bank_mask:0xf
	v_fmac_f32_dpp v121, v100, v39 row_newbcast:7 row_mask:0xf bank_mask:0xf
	v_fmac_f32_dpp v120, v100, v40 row_newbcast:8 row_mask:0xf bank_mask:0xf
	v_fmac_f32_dpp v121, v100, v41 row_newbcast:9 row_mask:0xf bank_mask:0xf
	v_fmac_f32_dpp v120, v100, v42 row_newbcast:10 row_mask:0xf bank_mask:0xf
	v_fmac_f32_dpp v121, v100, v43 row_newbcast:11 row_mask:0xf bank_mask:0xf
	v_fmac_f32_dpp v120, v100, v44 row_newbcast:12 row_mask:0xf bank_mask:0xf
	v_fmac_f32_dpp v121, v100, v45 row_newbcast:13 row_mask:0xf bank_mask:0xf
	v_fmac_f32_dpp v120, v100, v46 row_newbcast:14 row_mask:0xf bank_mask:0xf
	v_fmac_f32_dpp v121, v100, v47 row_newbcast:15 row_mask:0xf bank_mask:0xf
	v_mul_f32_dpp v122, v101, v48 row_newbcast:0 row_mask:0xf bank_mask:0xf
	v_mul_f32_dpp v123, v101, v49 row_newbcast:1 row_mask:0xf bank_mask:0xf
	v_fmac_f32_dpp v122, v101, v50 row_newbcast:2 row_mask:0xf bank_mask:0xf
	v_fmac_f32_dpp v123, v101, v51 row_newbcast:3 row_mask:0xf bank_mask:0xf
	v_fmac_f32_dpp v122, v101, v52 row_newbcast:4 row_mask:0xf bank_mask:0xf
	v_fmac_f32_dpp v123, v101, v53 row_newbcast:5 row_mask:0xf bank_mask:0xf
	v_fmac_f32_dpp v122, v101, v54 row_newbcast:6 row_mask:0xf bank_mask:0xf
	v_fmac_f32_dpp v123, v101, v55 row_newbcast:7 row_mask:0xf bank_mask:0xf
	v_fmac_f32_dpp v122, v101, v56 row_newbcast:8 row_mask:0xf bank_mask:0xf
	v_fmac_f32_dpp v123, v101, v57 row_newbcast:9 row_mask:0xf bank_mask:0xf
	v_fmac_f32_dpp v122, v101, v58 row_newbcast:10 row_mask:0xf bank_mask:0xf
	v_fmac_f32_dpp v123, v101, v59 row_newbcast:11 row_mask:0xf bank_mask:0xf
	v_fmac_f32_dpp v122, v101, v60 row_newbcast:12 row_mask:0xf bank_mask:0xf
	v_fmac_f32_dpp v123, v101, v61 row_newbcast:13 row_mask:0xf bank_mask:0xf
	v_fmac_f32_dpp v122, v101, v62 row_newbcast:14 row_mask:0xf bank_mask:0xf
	v_fmac_f32_dpp v123, v101, v63 row_newbcast:15 row_mask:0xf bank_mask:0xf
	v_add_f32_e32 v120, v120, v121
	v_add_f32_e32 v122, v122, v123
	v_add_f32_e32 v128, v120, v122
	s_nop 1
	v_permlane32_swap_b32 v129, v128
	s_mov_b32 exec_lo, 0
	v_add_f32_e64 v108, -v129, -v128
	s_mov_b32 exec_lo, -1
	s_nop 0
	v_mfma_f32_32x32x2_f32 v[64:79], v104, v108, v[32:47]
	s_nop 15
	v_mfma_f32_32x32x2_f32 v[80:95], v105, v108, v[48:63]
	s_nop 7
	s_waitcnt lgkmcnt(0)
	ds_read_b32 v100, v14 offset:15616
	ds_read_b32 v101, v14 offset:15744
	ds_read_b32 v104, v15 offset:15360
	ds_read_b32 v105, v15 offset:15488
	ds_read_b32 v108, v16 offset:15360
	ds_read_b32 v114, v14 offset:16384
	ds_read_b32 v115, v14 offset:16512
	v_mul_f32_dpp v120, v102, v64 row_newbcast:0 row_mask:0xf bank_mask:0xf
	v_mul_f32_dpp v121, v102, v65 row_newbcast:1 row_mask:0xf bank_mask:0xf
	v_fmac_f32_dpp v120, v102, v66 row_newbcast:2 row_mask:0xf bank_mask:0xf
	v_fmac_f32_dpp v121, v102, v67 row_newbcast:3 row_mask:0xf bank_mask:0xf
	v_fmac_f32_dpp v120, v102, v68 row_newbcast:4 row_mask:0xf bank_mask:0xf
	v_fmac_f32_dpp v121, v102, v69 row_newbcast:5 row_mask:0xf bank_mask:0xf
	v_fmac_f32_dpp v120, v102, v70 row_newbcast:6 row_mask:0xf bank_mask:0xf
	v_fmac_f32_dpp v121, v102, v71 row_newbcast:7 row_mask:0xf bank_mask:0xf
	v_fmac_f32_dpp v120, v102, v72 row_newbcast:8 row_mask:0xf bank_mask:0xf
	v_fmac_f32_dpp v121, v102, v73 row_newbcast:9 row_mask:0xf bank_mask:0xf
	v_fmac_f32_dpp v120, v102, v74 row_newbcast:10 row_mask:0xf bank_mask:0xf
	v_fmac_f32_dpp v121, v102, v75 row_newbcast:11 row_mask:0xf bank_mask:0xf
	v_fmac_f32_dpp v120, v102, v76 row_newbcast:12 row_mask:0xf bank_mask:0xf
	v_fmac_f32_dpp v121, v102, v77 row_newbcast:13 row_mask:0xf bank_mask:0xf
	v_fmac_f32_dpp v120, v102, v78 row_newbcast:14 row_mask:0xf bank_mask:0xf
	v_fmac_f32_dpp v121, v102, v79 row_newbcast:15 row_mask:0xf bank_mask:0xf
	v_mul_f32_dpp v122, v103, v80 row_newbcast:0 row_mask:0xf bank_mask:0xf
	v_mul_f32_dpp v123, v103, v81 row_newbcast:1 row_mask:0xf bank_mask:0xf
	v_fmac_f32_dpp v122, v103, v82 row_newbcast:2 row_mask:0xf bank_mask:0xf
	v_fmac_f32_dpp v123, v103, v83 row_newbcast:3 row_mask:0xf bank_mask:0xf
	v_fmac_f32_dpp v122, v103, v84 row_newbcast:4 row_mask:0xf bank_mask:0xf
	v_fmac_f32_dpp v123, v103, v85 row_newbcast:5 row_mask:0xf bank_mask:0xf
	v_fmac_f32_dpp v122, v103, v86 row_newbcast:6 row_mask:0xf bank_mask:0xf
	v_fmac_f32_dpp v123, v103, v87 row_newbcast:7 row_mask:0xf bank_mask:0xf
	v_fmac_f32_dpp v122, v103, v88 row_newbcast:8 row_mask:0xf bank_mask:0xf
	v_fmac_f32_dpp v123, v103, v89 row_newbcast:9 row_mask:0xf bank_mask:0xf
	v_fmac_f32_dpp v122, v103, v90 row_newbcast:10 row_mask:0xf bank_mask:0xf
	v_fmac_f32_dpp v123, v103, v91 row_newbcast:11 row_mask:0xf bank_mask:0xf
	v_fmac_f32_dpp v122, v103, v92 row_newbcast:12 row_mask:0xf bank_mask:0xf
	v_fmac_f32_dpp v123, v103, v93 row_newbcast:13 row_mask:0xf bank_mask:0xf
	v_fmac_f32_dpp v122, v103, v94 row_newbcast:14 row_mask:0xf bank_mask:0xf
	v_fmac_f32_dpp v123, v103, v95 row_newbcast:15 row_mask:0xf bank_mask:0xf
	v_add_f32_e32 v120, v120, v121
	v_add_f32_e32 v122, v122, v123
	v_add_f32_e32 v128, v120, v122
	s_nop 1
	v_permlane32_swap_b32 v129, v128
	s_mov_b32 exec_lo, 0
	v_add_f32_e64 v109, -v129, -v128
	s_mov_b32 exec_lo, -1
	s_nop 0
	v_mfma_f32_32x32x2_f32 v[32:47], v106, v109, v[64:79]
	v_mul_f32_dpp v124, v110, v64 row_newbcast:0 row_mask:0xf bank_mask:0xf
	v_mul_f32_dpp v125, v110, v65 row_newbcast:1 row_mask:0xf bank_mask:0xf
	v_fmac_f32_dpp v124, v110, v66 row_newbcast:2 row_mask:0xf bank_mask:0xf
	v_fmac_f32_dpp v125, v110, v67 row_newbcast:3 row_mask:0xf bank_mask:0xf
	v_fmac_f32_dpp v124, v110, v68 row_newbcast:4 row_mask:0xf bank_mask:0xf
	v_fmac_f32_dpp v125, v110, v69 row_newbcast:5 row_mask:0xf bank_mask:0xf
	v_fmac_f32_dpp v124, v110, v70 row_newbcast:6 row_mask:0xf bank_mask:0xf
	v_fmac_f32_dpp v125, v110, v71 row_newbcast:7 row_mask:0xf bank_mask:0xf
	v_fmac_f32_dpp v124, v110, v72 row_newbcast:8 row_mask:0xf bank_mask:0xf
	v_fmac_f32_dpp v125, v110, v73 row_newbcast:9 row_mask:0xf bank_mask:0xf
	v_fmac_f32_dpp v124, v110, v74 row_newbcast:10 row_mask:0xf bank_mask:0xf
	v_fmac_f32_dpp v125, v110, v75 row_newbcast:11 row_mask:0xf bank_mask:0xf
	v_fmac_f32_dpp v124, v110, v76 row_newbcast:12 row_mask:0xf bank_mask:0xf
	v_fmac_f32_dpp v125, v110, v77 row_newbcast:13 row_mask:0xf bank_mask:0xf
	v_fmac_f32_dpp v124, v110, v78 row_newbcast:14 row_mask:0xf bank_mask:0xf
	v_fmac_f32_dpp v125, v110, v79 row_newbcast:15 row_mask:0xf bank_mask:0xf
	v_mfma_f32_32x32x2_f32 v[48:63], v107, v109, v[80:95]
	v_mul_f32_dpp v126, v111, v80 row_newbcast:0 row_mask:0xf bank_mask:0xf
	v_mul_f32_dpp v127, v111, v81 row_newbcast:1 row_mask:0xf bank_mask:0xf
	v_fmac_f32_dpp v126, v111, v82 row_newbcast:2 row_mask:0xf bank_mask:0xf
	v_fmac_f32_dpp v127, v111, v83 row_newbcast:3 row_mask:0xf bank_mask:0xf
	v_fmac_f32_dpp v126, v111, v84 row_newbcast:4 row_mask:0xf bank_mask:0xf
	v_fmac_f32_dpp v127, v111, v85 row_newbcast:5 row_mask:0xf bank_mask:0xf
	v_fmac_f32_dpp v126, v111, v86 row_newbcast:6 row_mask:0xf bank_mask:0xf
	v_fmac_f32_dpp v127, v111, v87 row_newbcast:7 row_mask:0xf bank_mask:0xf
	v_fmac_f32_dpp v126, v111, v88 row_newbcast:8 row_mask:0xf bank_mask:0xf
	v_fmac_f32_dpp v127, v111, v89 row_newbcast:9 row_mask:0xf bank_mask:0xf
	v_fmac_f32_dpp v126, v111, v90 row_newbcast:10 row_mask:0xf bank_mask:0xf
	v_fmac_f32_dpp v127, v111, v91 row_newbcast:11 row_mask:0xf bank_mask:0xf
	v_fmac_f32_dpp v126, v111, v92 row_newbcast:12 row_mask:0xf bank_mask:0xf
	v_fmac_f32_dpp v127, v111, v93 row_newbcast:13 row_mask:0xf bank_mask:0xf
	v_fmac_f32_dpp v126, v111, v94 row_newbcast:14 row_mask:0xf bank_mask:0xf
	v_fmac_f32_dpp v127, v111, v95 row_newbcast:15 row_mask:0xf bank_mask:0xf
	v_add_f32_e32 v124, v124, v125
	v_add_f32_e32 v126, v126, v127
	v_add_f32_e32 v130, v124, v126
	s_nop 1
	v_permlane32_swap_b32 v131, v130
	s_mov_b32 exec_lo, 0
	v_add_f32_e32 v133, v131, v130
	v_cvt_pk_bf16_f32 v133, v133, v133
	global_store_short v13, v133, s[16:17]
	s_mov_b32 exec_lo, -1
	s_add_u32 s16, s16, s20
	s_addc_u32 s17, s17, s21
	s_waitcnt lgkmcnt(0)
	ds_read_b32 v102, v14 offset:17152
	ds_read_b32 v103, v14 offset:17280
	ds_read_b32 v106, v15 offset:16896
	ds_read_b32 v107, v15 offset:17024
	ds_read_b32 v109, v16 offset:16896
	ds_read_b32 v116, v14 offset:17920
	ds_read_b32 v117, v14 offset:18048
	v_mul_f32_dpp v120, v100, v32 row_newbcast:0 row_mask:0xf bank_mask:0xf
	v_mul_f32_dpp v121, v100, v33 row_newbcast:1 row_mask:0xf bank_mask:0xf
	v_fmac_f32_dpp v120, v100, v34 row_newbcast:2 row_mask:0xf bank_mask:0xf
	v_fmac_f32_dpp v121, v100, v35 row_newbcast:3 row_mask:0xf bank_mask:0xf
	v_fmac_f32_dpp v120, v100, v36 row_newbcast:4 row_mask:0xf bank_mask:0xf
	v_fmac_f32_dpp v121, v100, v37 row_newbcast:5 row_mask:0xf bank_mask:0xf
	v_fmac_f32_dpp v120, v100, v38 row_newbcast:6 row_mask:0xf bank_mask:0xf
	v_fmac_f32_dpp v121, v100, v39 row_newbcast:7 row_mask:0xf bank_mask:0xf
	v_fmac_f32_dpp v120, v100, v40 row_newbcast:8 row_mask:0xf bank_mask:0xf
	v_fmac_f32_dpp v121, v100, v41 row_newbcast:9 row_mask:0xf bank_mask:0xf
	v_fmac_f32_dpp v120, v100, v42 row_newbcast:10 row_mask:0xf bank_mask:0xf
	v_fmac_f32_dpp v121, v100, v43 row_newbcast:11 row_mask:0xf bank_mask:0xf
	v_fmac_f32_dpp v120, v100, v44 row_newbcast:12 row_mask:0xf bank_mask:0xf
	v_fmac_f32_dpp v121, v100, v45 row_newbcast:13 row_mask:0xf bank_mask:0xf
	v_fmac_f32_dpp v120, v100, v46 row_newbcast:14 row_mask:0xf bank_mask:0xf
	v_fmac_f32_dpp v121, v100, v47 row_newbcast:15 row_mask:0xf bank_mask:0xf
	v_mul_f32_dpp v122, v101, v48 row_newbcast:0 row_mask:0xf bank_mask:0xf
	v_mul_f32_dpp v123, v101, v49 row_newbcast:1 row_mask:0xf bank_mask:0xf
	v_fmac_f32_dpp v122, v101, v50 row_newbcast:2 row_mask:0xf bank_mask:0xf
	v_fmac_f32_dpp v123, v101, v51 row_newbcast:3 row_mask:0xf bank_mask:0xf
	v_fmac_f32_dpp v122, v101, v52 row_newbcast:4 row_mask:0xf bank_mask:0xf
	v_fmac_f32_dpp v123, v101, v53 row_newbcast:5 row_mask:0xf bank_mask:0xf
	v_fmac_f32_dpp v122, v101, v54 row_newbcast:6 row_mask:0xf bank_mask:0xf
	v_fmac_f32_dpp v123, v101, v55 row_newbcast:7 row_mask:0xf bank_mask:0xf
	v_fmac_f32_dpp v122, v101, v56 row_newbcast:8 row_mask:0xf bank_mask:0xf
	v_fmac_f32_dpp v123, v101, v57 row_newbcast:9 row_mask:0xf bank_mask:0xf
	v_fmac_f32_dpp v122, v101, v58 row_newbcast:10 row_mask:0xf bank_mask:0xf
	v_fmac_f32_dpp v123, v101, v59 row_newbcast:11 row_mask:0xf bank_mask:0xf
	v_fmac_f32_dpp v122, v101, v60 row_newbcast:12 row_mask:0xf bank_mask:0xf
	v_fmac_f32_dpp v123, v101, v61 row_newbcast:13 row_mask:0xf bank_mask:0xf
	v_fmac_f32_dpp v122, v101, v62 row_newbcast:14 row_mask:0xf bank_mask:0xf
	v_fmac_f32_dpp v123, v101, v63 row_newbcast:15 row_mask:0xf bank_mask:0xf
	v_add_f32_e32 v120, v120, v121
	v_add_f32_e32 v122, v122, v123
	v_add_f32_e32 v128, v120, v122
	s_nop 1
	v_permlane32_swap_b32 v129, v128
	s_mov_b32 exec_lo, 0
	v_add_f32_e64 v108, -v129, -v128
	s_mov_b32 exec_lo, -1
	s_nop 0
	v_mfma_f32_32x32x2_f32 v[64:79], v104, v108, v[32:47]
	v_mul_f32_dpp v124, v112, v32 row_newbcast:0 row_mask:0xf bank_mask:0xf
	v_mul_f32_dpp v125, v112, v33 row_newbcast:1 row_mask:0xf bank_mask:0xf
	v_fmac_f32_dpp v124, v112, v34 row_newbcast:2 row_mask:0xf bank_mask:0xf
	v_fmac_f32_dpp v125, v112, v35 row_newbcast:3 row_mask:0xf bank_mask:0xf
	v_fmac_f32_dpp v124, v112, v36 row_newbcast:4 row_mask:0xf bank_mask:0xf
	v_fmac_f32_dpp v125, v112, v37 row_newbcast:5 row_mask:0xf bank_mask:0xf
	v_fmac_f32_dpp v124, v112, v38 row_newbcast:6 row_mask:0xf bank_mask:0xf
	v_fmac_f32_dpp v125, v112, v39 row_newbcast:7 row_mask:0xf bank_mask:0xf
	v_fmac_f32_dpp v124, v112, v40 row_newbcast:8 row_mask:0xf bank_mask:0xf
	v_fmac_f32_dpp v125, v112, v41 row_newbcast:9 row_mask:0xf bank_mask:0xf
	v_fmac_f32_dpp v124, v112, v42 row_newbcast:10 row_mask:0xf bank_mask:0xf
	v_fmac_f32_dpp v125, v112, v43 row_newbcast:11 row_mask:0xf bank_mask:0xf
	v_fmac_f32_dpp v124, v112, v44 row_newbcast:12 row_mask:0xf bank_mask:0xf
	v_fmac_f32_dpp v125, v112, v45 row_newbcast:13 row_mask:0xf bank_mask:0xf
	v_fmac_f32_dpp v124, v112, v46 row_newbcast:14 row_mask:0xf bank_mask:0xf
	v_fmac_f32_dpp v125, v112, v47 row_newbcast:15 row_mask:0xf bank_mask:0xf
	v_mfma_f32_32x32x2_f32 v[80:95], v105, v108, v[48:63]
	v_mul_f32_dpp v126, v113, v48 row_newbcast:0 row_mask:0xf bank_mask:0xf
	v_mul_f32_dpp v127, v113, v49 row_newbcast:1 row_mask:0xf bank_mask:0xf
	v_fmac_f32_dpp v126, v113, v50 row_newbcast:2 row_mask:0xf bank_mask:0xf
	v_fmac_f32_dpp v127, v113, v51 row_newbcast:3 row_mask:0xf bank_mask:0xf
	v_fmac_f32_dpp v126, v113, v52 row_newbcast:4 row_mask:0xf bank_mask:0xf
	v_fmac_f32_dpp v127, v113, v53 row_newbcast:5 row_mask:0xf bank_mask:0xf
	v_fmac_f32_dpp v126, v113, v54 row_newbcast:6 row_mask:0xf bank_mask:0xf
	v_fmac_f32_dpp v127, v113, v55 row_newbcast:7 row_mask:0xf bank_mask:0xf
	v_fmac_f32_dpp v126, v113, v56 row_newbcast:8 row_mask:0xf bank_mask:0xf
	v_fmac_f32_dpp v127, v113, v57 row_newbcast:9 row_mask:0xf bank_mask:0xf
	v_fmac_f32_dpp v126, v113, v58 row_newbcast:10 row_mask:0xf bank_mask:0xf
	v_fmac_f32_dpp v127, v113, v59 row_newbcast:11 row_mask:0xf bank_mask:0xf
	v_fmac_f32_dpp v126, v113, v60 row_newbcast:12 row_mask:0xf bank_mask:0xf
	v_fmac_f32_dpp v127, v113, v61 row_newbcast:13 row_mask:0xf bank_mask:0xf
	v_fmac_f32_dpp v126, v113, v62 row_newbcast:14 row_mask:0xf bank_mask:0xf
	v_fmac_f32_dpp v127, v113, v63 row_newbcast:15 row_mask:0xf bank_mask:0xf
	v_add_f32_e32 v124, v124, v125
	v_add_f32_e32 v126, v126, v127
	v_add_f32_e32 v130, v124, v126
	s_nop 1
	v_permlane32_swap_b32 v131, v130
	s_mov_b32 exec_lo, 0
	v_add_f32_e32 v133, v131, v130
	v_cvt_pk_bf16_f32 v133, v133, v133
	global_store_short v13, v133, s[16:17]
	s_mov_b32 exec_lo, -1
	s_add_u32 s16, s16, s20
	s_addc_u32 s17, s17, s21
	s_waitcnt lgkmcnt(0)
	ds_read_b32 v100, v14 offset:18688
	ds_read_b32 v101, v14 offset:18816
	ds_read_b32 v104, v15 offset:18432
	ds_read_b32 v105, v15 offset:18560
	ds_read_b32 v108, v16 offset:18432
	ds_read_b32 v110, v14 offset:19456
	ds_read_b32 v111, v14 offset:19584
	v_mul_f32_dpp v120, v102, v64 row_newbcast:0 row_mask:0xf bank_mask:0xf
	v_mul_f32_dpp v121, v102, v65 row_newbcast:1 row_mask:0xf bank_mask:0xf
	v_fmac_f32_dpp v120, v102, v66 row_newbcast:2 row_mask:0xf bank_mask:0xf
	v_fmac_f32_dpp v121, v102, v67 row_newbcast:3 row_mask:0xf bank_mask:0xf
	v_fmac_f32_dpp v120, v102, v68 row_newbcast:4 row_mask:0xf bank_mask:0xf
	v_fmac_f32_dpp v121, v102, v69 row_newbcast:5 row_mask:0xf bank_mask:0xf
	v_fmac_f32_dpp v120, v102, v70 row_newbcast:6 row_mask:0xf bank_mask:0xf
	v_fmac_f32_dpp v121, v102, v71 row_newbcast:7 row_mask:0xf bank_mask:0xf
	v_fmac_f32_dpp v120, v102, v72 row_newbcast:8 row_mask:0xf bank_mask:0xf
	v_fmac_f32_dpp v121, v102, v73 row_newbcast:9 row_mask:0xf bank_mask:0xf
	v_fmac_f32_dpp v120, v102, v74 row_newbcast:10 row_mask:0xf bank_mask:0xf
	v_fmac_f32_dpp v121, v102, v75 row_newbcast:11 row_mask:0xf bank_mask:0xf
	v_fmac_f32_dpp v120, v102, v76 row_newbcast:12 row_mask:0xf bank_mask:0xf
	v_fmac_f32_dpp v121, v102, v77 row_newbcast:13 row_mask:0xf bank_mask:0xf
	v_fmac_f32_dpp v120, v102, v78 row_newbcast:14 row_mask:0xf bank_mask:0xf
	v_fmac_f32_dpp v121, v102, v79 row_newbcast:15 row_mask:0xf bank_mask:0xf
	v_mul_f32_dpp v122, v103, v80 row_newbcast:0 row_mask:0xf bank_mask:0xf
	v_mul_f32_dpp v123, v103, v81 row_newbcast:1 row_mask:0xf bank_mask:0xf
	v_fmac_f32_dpp v122, v103, v82 row_newbcast:2 row_mask:0xf bank_mask:0xf
	v_fmac_f32_dpp v123, v103, v83 row_newbcast:3 row_mask:0xf bank_mask:0xf
	v_fmac_f32_dpp v122, v103, v84 row_newbcast:4 row_mask:0xf bank_mask:0xf
	v_fmac_f32_dpp v123, v103, v85 row_newbcast:5 row_mask:0xf bank_mask:0xf
	v_fmac_f32_dpp v122, v103, v86 row_newbcast:6 row_mask:0xf bank_mask:0xf
	v_fmac_f32_dpp v123, v103, v87 row_newbcast:7 row_mask:0xf bank_mask:0xf
	v_fmac_f32_dpp v122, v103, v88 row_newbcast:8 row_mask:0xf bank_mask:0xf
	v_fmac_f32_dpp v123, v103, v89 row_newbcast:9 row_mask:0xf bank_mask:0xf
	v_fmac_f32_dpp v122, v103, v90 row_newbcast:10 row_mask:0xf bank_mask:0xf
	v_fmac_f32_dpp v123, v103, v91 row_newbcast:11 row_mask:0xf bank_mask:0xf
	v_fmac_f32_dpp v122, v103, v92 row_newbcast:12 row_mask:0xf bank_mask:0xf
	v_fmac_f32_dpp v123, v103, v93 row_newbcast:13 row_mask:0xf bank_mask:0xf
	v_fmac_f32_dpp v122, v103, v94 row_newbcast:14 row_mask:0xf bank_mask:0xf
	v_fmac_f32_dpp v123, v103, v95 row_newbcast:15 row_mask:0xf bank_mask:0xf
	v_add_f32_e32 v120, v120, v121
	v_add_f32_e32 v122, v122, v123
	v_add_f32_e32 v128, v120, v122
	s_nop 1
	v_permlane32_swap_b32 v129, v128
	s_mov_b32 exec_lo, 0
	v_add_f32_e64 v109, -v129, -v128
	s_mov_b32 exec_lo, -1
	s_nop 0
	v_mfma_f32_32x32x2_f32 v[32:47], v106, v109, v[64:79]
	v_mul_f32_dpp v124, v114, v64 row_newbcast:0 row_mask:0xf bank_mask:0xf
	v_mul_f32_dpp v125, v114, v65 row_newbcast:1 row_mask:0xf bank_mask:0xf
	v_fmac_f32_dpp v124, v114, v66 row_newbcast:2 row_mask:0xf bank_mask:0xf
	v_fmac_f32_dpp v125, v114, v67 row_newbcast:3 row_mask:0xf bank_mask:0xf
	v_fmac_f32_dpp v124, v114, v68 row_newbcast:4 row_mask:0xf bank_mask:0xf
	v_fmac_f32_dpp v125, v114, v69 row_newbcast:5 row_mask:0xf bank_mask:0xf
	v_fmac_f32_dpp v124, v114, v70 row_newbcast:6 row_mask:0xf bank_mask:0xf
	v_fmac_f32_dpp v125, v114, v71 row_newbcast:7 row_mask:0xf bank_mask:0xf
	v_fmac_f32_dpp v124, v114, v72 row_newbcast:8 row_mask:0xf bank_mask:0xf
	v_fmac_f32_dpp v125, v114, v73 row_newbcast:9 row_mask:0xf bank_mask:0xf
	v_fmac_f32_dpp v124, v114, v74 row_newbcast:10 row_mask:0xf bank_mask:0xf
	v_fmac_f32_dpp v125, v114, v75 row_newbcast:11 row_mask:0xf bank_mask:0xf
	v_fmac_f32_dpp v124, v114, v76 row_newbcast:12 row_mask:0xf bank_mask:0xf
	v_fmac_f32_dpp v125, v114, v77 row_newbcast:13 row_mask:0xf bank_mask:0xf
	v_fmac_f32_dpp v124, v114, v78 row_newbcast:14 row_mask:0xf bank_mask:0xf
	v_fmac_f32_dpp v125, v114, v79 row_newbcast:15 row_mask:0xf bank_mask:0xf
	v_mfma_f32_32x32x2_f32 v[48:63], v107, v109, v[80:95]
	v_mul_f32_dpp v126, v115, v80 row_newbcast:0 row_mask:0xf bank_mask:0xf
	v_mul_f32_dpp v127, v115, v81 row_newbcast:1 row_mask:0xf bank_mask:0xf
	v_fmac_f32_dpp v126, v115, v82 row_newbcast:2 row_mask:0xf bank_mask:0xf
	v_fmac_f32_dpp v127, v115, v83 row_newbcast:3 row_mask:0xf bank_mask:0xf
	v_fmac_f32_dpp v126, v115, v84 row_newbcast:4 row_mask:0xf bank_mask:0xf
	v_fmac_f32_dpp v127, v115, v85 row_newbcast:5 row_mask:0xf bank_mask:0xf
	v_fmac_f32_dpp v126, v115, v86 row_newbcast:6 row_mask:0xf bank_mask:0xf
	v_fmac_f32_dpp v127, v115, v87 row_newbcast:7 row_mask:0xf bank_mask:0xf
	v_fmac_f32_dpp v126, v115, v88 row_newbcast:8 row_mask:0xf bank_mask:0xf
	v_fmac_f32_dpp v127, v115, v89 row_newbcast:9 row_mask:0xf bank_mask:0xf
	v_fmac_f32_dpp v126, v115, v90 row_newbcast:10 row_mask:0xf bank_mask:0xf
	v_fmac_f32_dpp v127, v115, v91 row_newbcast:11 row_mask:0xf bank_mask:0xf
	v_fmac_f32_dpp v126, v115, v92 row_newbcast:12 row_mask:0xf bank_mask:0xf
	v_fmac_f32_dpp v127, v115, v93 row_newbcast:13 row_mask:0xf bank_mask:0xf
	v_fmac_f32_dpp v126, v115, v94 row_newbcast:14 row_mask:0xf bank_mask:0xf
	v_fmac_f32_dpp v127, v115, v95 row_newbcast:15 row_mask:0xf bank_mask:0xf
	v_add_f32_e32 v124, v124, v125
	v_add_f32_e32 v126, v126, v127
	v_add_f32_e32 v130, v124, v126
	s_nop 1
	v_permlane32_swap_b32 v131, v130
	s_mov_b32 exec_lo, 0
	v_add_f32_e32 v133, v131, v130
	v_cvt_pk_bf16_f32 v133, v133, v133
	global_store_short v13, v133, s[16:17]
	s_mov_b32 exec_lo, -1
	s_add_u32 s16, s16, s20
	s_addc_u32 s17, s17, s21
	s_waitcnt lgkmcnt(0)
	ds_read_b32 v102, v14 offset:20224
	ds_read_b32 v103, v14 offset:20352
	ds_read_b32 v106, v15 offset:19968
	ds_read_b32 v107, v15 offset:20096
	ds_read_b32 v109, v16 offset:19968
	ds_read_b32 v112, v14 offset:20992
	ds_read_b32 v113, v14 offset:21120
	v_mul_f32_dpp v120, v100, v32 row_newbcast:0 row_mask:0xf bank_mask:0xf
	v_mul_f32_dpp v121, v100, v33 row_newbcast:1 row_mask:0xf bank_mask:0xf
	v_fmac_f32_dpp v120, v100, v34 row_newbcast:2 row_mask:0xf bank_mask:0xf
	v_fmac_f32_dpp v121, v100, v35 row_newbcast:3 row_mask:0xf bank_mask:0xf
	v_fmac_f32_dpp v120, v100, v36 row_newbcast:4 row_mask:0xf bank_mask:0xf
	v_fmac_f32_dpp v121, v100, v37 row_newbcast:5 row_mask:0xf bank_mask:0xf
	v_fmac_f32_dpp v120, v100, v38 row_newbcast:6 row_mask:0xf bank_mask:0xf
	v_fmac_f32_dpp v121, v100, v39 row_newbcast:7 row_mask:0xf bank_mask:0xf
	v_fmac_f32_dpp v120, v100, v40 row_newbcast:8 row_mask:0xf bank_mask:0xf
	v_fmac_f32_dpp v121, v100, v41 row_newbcast:9 row_mask:0xf bank_mask:0xf
	v_fmac_f32_dpp v120, v100, v42 row_newbcast:10 row_mask:0xf bank_mask:0xf
	v_fmac_f32_dpp v121, v100, v43 row_newbcast:11 row_mask:0xf bank_mask:0xf
	v_fmac_f32_dpp v120, v100, v44 row_newbcast:12 row_mask:0xf bank_mask:0xf
	v_fmac_f32_dpp v121, v100, v45 row_newbcast:13 row_mask:0xf bank_mask:0xf
	v_fmac_f32_dpp v120, v100, v46 row_newbcast:14 row_mask:0xf bank_mask:0xf
	v_fmac_f32_dpp v121, v100, v47 row_newbcast:15 row_mask:0xf bank_mask:0xf
	v_mul_f32_dpp v122, v101, v48 row_newbcast:0 row_mask:0xf bank_mask:0xf
	v_mul_f32_dpp v123, v101, v49 row_newbcast:1 row_mask:0xf bank_mask:0xf
	v_fmac_f32_dpp v122, v101, v50 row_newbcast:2 row_mask:0xf bank_mask:0xf
	v_fmac_f32_dpp v123, v101, v51 row_newbcast:3 row_mask:0xf bank_mask:0xf
	v_fmac_f32_dpp v122, v101, v52 row_newbcast:4 row_mask:0xf bank_mask:0xf
	v_fmac_f32_dpp v123, v101, v53 row_newbcast:5 row_mask:0xf bank_mask:0xf
	v_fmac_f32_dpp v122, v101, v54 row_newbcast:6 row_mask:0xf bank_mask:0xf
	v_fmac_f32_dpp v123, v101, v55 row_newbcast:7 row_mask:0xf bank_mask:0xf
	v_fmac_f32_dpp v122, v101, v56 row_newbcast:8 row_mask:0xf bank_mask:0xf
	v_fmac_f32_dpp v123, v101, v57 row_newbcast:9 row_mask:0xf bank_mask:0xf
	v_fmac_f32_dpp v122, v101, v58 row_newbcast:10 row_mask:0xf bank_mask:0xf
	v_fmac_f32_dpp v123, v101, v59 row_newbcast:11 row_mask:0xf bank_mask:0xf
	v_fmac_f32_dpp v122, v101, v60 row_newbcast:12 row_mask:0xf bank_mask:0xf
	v_fmac_f32_dpp v123, v101, v61 row_newbcast:13 row_mask:0xf bank_mask:0xf
	v_fmac_f32_dpp v122, v101, v62 row_newbcast:14 row_mask:0xf bank_mask:0xf
	v_fmac_f32_dpp v123, v101, v63 row_newbcast:15 row_mask:0xf bank_mask:0xf
	v_add_f32_e32 v120, v120, v121
	v_add_f32_e32 v122, v122, v123
	v_add_f32_e32 v128, v120, v122
	s_nop 1
	v_permlane32_swap_b32 v129, v128
	s_mov_b32 exec_lo, 0
	v_add_f32_e64 v108, -v129, -v128
	s_mov_b32 exec_lo, -1
	s_nop 0
	v_mfma_f32_32x32x2_f32 v[64:79], v104, v108, v[32:47]
	v_mul_f32_dpp v124, v116, v32 row_newbcast:0 row_mask:0xf bank_mask:0xf
	v_mul_f32_dpp v125, v116, v33 row_newbcast:1 row_mask:0xf bank_mask:0xf
	v_fmac_f32_dpp v124, v116, v34 row_newbcast:2 row_mask:0xf bank_mask:0xf
	v_fmac_f32_dpp v125, v116, v35 row_newbcast:3 row_mask:0xf bank_mask:0xf
	v_fmac_f32_dpp v124, v116, v36 row_newbcast:4 row_mask:0xf bank_mask:0xf
	v_fmac_f32_dpp v125, v116, v37 row_newbcast:5 row_mask:0xf bank_mask:0xf
	v_fmac_f32_dpp v124, v116, v38 row_newbcast:6 row_mask:0xf bank_mask:0xf
	v_fmac_f32_dpp v125, v116, v39 row_newbcast:7 row_mask:0xf bank_mask:0xf
	v_fmac_f32_dpp v124, v116, v40 row_newbcast:8 row_mask:0xf bank_mask:0xf
	v_fmac_f32_dpp v125, v116, v41 row_newbcast:9 row_mask:0xf bank_mask:0xf
	v_fmac_f32_dpp v124, v116, v42 row_newbcast:10 row_mask:0xf bank_mask:0xf
	v_fmac_f32_dpp v125, v116, v43 row_newbcast:11 row_mask:0xf bank_mask:0xf
	v_fmac_f32_dpp v124, v116, v44 row_newbcast:12 row_mask:0xf bank_mask:0xf
	v_fmac_f32_dpp v125, v116, v45 row_newbcast:13 row_mask:0xf bank_mask:0xf
	v_fmac_f32_dpp v124, v116, v46 row_newbcast:14 row_mask:0xf bank_mask:0xf
	v_fmac_f32_dpp v125, v116, v47 row_newbcast:15 row_mask:0xf bank_mask:0xf
	v_mfma_f32_32x32x2_f32 v[80:95], v105, v108, v[48:63]
	v_mul_f32_dpp v126, v117, v48 row_newbcast:0 row_mask:0xf bank_mask:0xf
	v_mul_f32_dpp v127, v117, v49 row_newbcast:1 row_mask:0xf bank_mask:0xf
	v_fmac_f32_dpp v126, v117, v50 row_newbcast:2 row_mask:0xf bank_mask:0xf
	v_fmac_f32_dpp v127, v117, v51 row_newbcast:3 row_mask:0xf bank_mask:0xf
	v_fmac_f32_dpp v126, v117, v52 row_newbcast:4 row_mask:0xf bank_mask:0xf
	v_fmac_f32_dpp v127, v117, v53 row_newbcast:5 row_mask:0xf bank_mask:0xf
	v_fmac_f32_dpp v126, v117, v54 row_newbcast:6 row_mask:0xf bank_mask:0xf
	v_fmac_f32_dpp v127, v117, v55 row_newbcast:7 row_mask:0xf bank_mask:0xf
	v_fmac_f32_dpp v126, v117, v56 row_newbcast:8 row_mask:0xf bank_mask:0xf
	v_fmac_f32_dpp v127, v117, v57 row_newbcast:9 row_mask:0xf bank_mask:0xf
	v_fmac_f32_dpp v126, v117, v58 row_newbcast:10 row_mask:0xf bank_mask:0xf
	v_fmac_f32_dpp v127, v117, v59 row_newbcast:11 row_mask:0xf bank_mask:0xf
	v_fmac_f32_dpp v126, v117, v60 row_newbcast:12 row_mask:0xf bank_mask:0xf
	v_fmac_f32_dpp v127, v117, v61 row_newbcast:13 row_mask:0xf bank_mask:0xf
	v_fmac_f32_dpp v126, v117, v62 row_newbcast:14 row_mask:0xf bank_mask:0xf
	v_fmac_f32_dpp v127, v117, v63 row_newbcast:15 row_mask:0xf bank_mask:0xf
	v_add_f32_e32 v124, v124, v125
	v_add_f32_e32 v126, v126, v127
	v_add_f32_e32 v130, v124, v126
	s_nop 1
	v_permlane32_swap_b32 v131, v130
	s_mov_b32 exec_lo, 0
	v_add_f32_e32 v133, v131, v130
	v_cvt_pk_bf16_f32 v133, v133, v133
	global_store_short v13, v133, s[16:17]
	s_mov_b32 exec_lo, -1
	s_add_u32 s16, s16, s20
	s_addc_u32 s17, s17, s21
	s_waitcnt lgkmcnt(0)
	ds_read_b32 v100, v14 offset:21760
	ds_read_b32 v101, v14 offset:21888
	ds_read_b32 v104, v15 offset:21504
	ds_read_b32 v105, v15 offset:21632
	ds_read_b32 v108, v16 offset:21504
	ds_read_b32 v114, v14 offset:22528
	ds_read_b32 v115, v14 offset:22656
	v_mul_f32_dpp v120, v102, v64 row_newbcast:0 row_mask:0xf bank_mask:0xf
	v_mul_f32_dpp v121, v102, v65 row_newbcast:1 row_mask:0xf bank_mask:0xf
	v_fmac_f32_dpp v120, v102, v66 row_newbcast:2 row_mask:0xf bank_mask:0xf
	v_fmac_f32_dpp v121, v102, v67 row_newbcast:3 row_mask:0xf bank_mask:0xf
	v_fmac_f32_dpp v120, v102, v68 row_newbcast:4 row_mask:0xf bank_mask:0xf
	v_fmac_f32_dpp v121, v102, v69 row_newbcast:5 row_mask:0xf bank_mask:0xf
	v_fmac_f32_dpp v120, v102, v70 row_newbcast:6 row_mask:0xf bank_mask:0xf
	v_fmac_f32_dpp v121, v102, v71 row_newbcast:7 row_mask:0xf bank_mask:0xf
	v_fmac_f32_dpp v120, v102, v72 row_newbcast:8 row_mask:0xf bank_mask:0xf
	v_fmac_f32_dpp v121, v102, v73 row_newbcast:9 row_mask:0xf bank_mask:0xf
	v_fmac_f32_dpp v120, v102, v74 row_newbcast:10 row_mask:0xf bank_mask:0xf
	v_fmac_f32_dpp v121, v102, v75 row_newbcast:11 row_mask:0xf bank_mask:0xf
	v_fmac_f32_dpp v120, v102, v76 row_newbcast:12 row_mask:0xf bank_mask:0xf
	v_fmac_f32_dpp v121, v102, v77 row_newbcast:13 row_mask:0xf bank_mask:0xf
	v_fmac_f32_dpp v120, v102, v78 row_newbcast:14 row_mask:0xf bank_mask:0xf
	v_fmac_f32_dpp v121, v102, v79 row_newbcast:15 row_mask:0xf bank_mask:0xf
	v_mul_f32_dpp v122, v103, v80 row_newbcast:0 row_mask:0xf bank_mask:0xf
	v_mul_f32_dpp v123, v103, v81 row_newbcast:1 row_mask:0xf bank_mask:0xf
	v_fmac_f32_dpp v122, v103, v82 row_newbcast:2 row_mask:0xf bank_mask:0xf
	v_fmac_f32_dpp v123, v103, v83 row_newbcast:3 row_mask:0xf bank_mask:0xf
	v_fmac_f32_dpp v122, v103, v84 row_newbcast:4 row_mask:0xf bank_mask:0xf
	v_fmac_f32_dpp v123, v103, v85 row_newbcast:5 row_mask:0xf bank_mask:0xf
	v_fmac_f32_dpp v122, v103, v86 row_newbcast:6 row_mask:0xf bank_mask:0xf
	v_fmac_f32_dpp v123, v103, v87 row_newbcast:7 row_mask:0xf bank_mask:0xf
	v_fmac_f32_dpp v122, v103, v88 row_newbcast:8 row_mask:0xf bank_mask:0xf
	v_fmac_f32_dpp v123, v103, v89 row_newbcast:9 row_mask:0xf bank_mask:0xf
	v_fmac_f32_dpp v122, v103, v90 row_newbcast:10 row_mask:0xf bank_mask:0xf
	v_fmac_f32_dpp v123, v103, v91 row_newbcast:11 row_mask:0xf bank_mask:0xf
	v_fmac_f32_dpp v122, v103, v92 row_newbcast:12 row_mask:0xf bank_mask:0xf
	v_fmac_f32_dpp v123, v103, v93 row_newbcast:13 row_mask:0xf bank_mask:0xf
	v_fmac_f32_dpp v122, v103, v94 row_newbcast:14 row_mask:0xf bank_mask:0xf
	v_fmac_f32_dpp v123, v103, v95 row_newbcast:15 row_mask:0xf bank_mask:0xf
	v_add_f32_e32 v120, v120, v121
	v_add_f32_e32 v122, v122, v123
	v_add_f32_e32 v128, v120, v122
	s_nop 1
	v_permlane32_swap_b32 v129, v128
	s_mov_b32 exec_lo, 0
	v_add_f32_e64 v109, -v129, -v128
	s_mov_b32 exec_lo, -1
	s_nop 0
	v_mfma_f32_32x32x2_f32 v[32:47], v106, v109, v[64:79]
	v_mul_f32_dpp v124, v110, v64 row_newbcast:0 row_mask:0xf bank_mask:0xf
	v_mul_f32_dpp v125, v110, v65 row_newbcast:1 row_mask:0xf bank_mask:0xf
	v_fmac_f32_dpp v124, v110, v66 row_newbcast:2 row_mask:0xf bank_mask:0xf
	v_fmac_f32_dpp v125, v110, v67 row_newbcast:3 row_mask:0xf bank_mask:0xf
	v_fmac_f32_dpp v124, v110, v68 row_newbcast:4 row_mask:0xf bank_mask:0xf
	v_fmac_f32_dpp v125, v110, v69 row_newbcast:5 row_mask:0xf bank_mask:0xf
	v_fmac_f32_dpp v124, v110, v70 row_newbcast:6 row_mask:0xf bank_mask:0xf
	v_fmac_f32_dpp v125, v110, v71 row_newbcast:7 row_mask:0xf bank_mask:0xf
	v_fmac_f32_dpp v124, v110, v72 row_newbcast:8 row_mask:0xf bank_mask:0xf
	v_fmac_f32_dpp v125, v110, v73 row_newbcast:9 row_mask:0xf bank_mask:0xf
	v_fmac_f32_dpp v124, v110, v74 row_newbcast:10 row_mask:0xf bank_mask:0xf
	v_fmac_f32_dpp v125, v110, v75 row_newbcast:11 row_mask:0xf bank_mask:0xf
	v_fmac_f32_dpp v124, v110, v76 row_newbcast:12 row_mask:0xf bank_mask:0xf
	v_fmac_f32_dpp v125, v110, v77 row_newbcast:13 row_mask:0xf bank_mask:0xf
	v_fmac_f32_dpp v124, v110, v78 row_newbcast:14 row_mask:0xf bank_mask:0xf
	v_fmac_f32_dpp v125, v110, v79 row_newbcast:15 row_mask:0xf bank_mask:0xf
	v_mfma_f32_32x32x2_f32 v[48:63], v107, v109, v[80:95]
	v_mul_f32_dpp v126, v111, v80 row_newbcast:0 row_mask:0xf bank_mask:0xf
	v_mul_f32_dpp v127, v111, v81 row_newbcast:1 row_mask:0xf bank_mask:0xf
	v_fmac_f32_dpp v126, v111, v82 row_newbcast:2 row_mask:0xf bank_mask:0xf
	v_fmac_f32_dpp v127, v111, v83 row_newbcast:3 row_mask:0xf bank_mask:0xf
	v_fmac_f32_dpp v126, v111, v84 row_newbcast:4 row_mask:0xf bank_mask:0xf
	v_fmac_f32_dpp v127, v111, v85 row_newbcast:5 row_mask:0xf bank_mask:0xf
	v_fmac_f32_dpp v126, v111, v86 row_newbcast:6 row_mask:0xf bank_mask:0xf
	v_fmac_f32_dpp v127, v111, v87 row_newbcast:7 row_mask:0xf bank_mask:0xf
	v_fmac_f32_dpp v126, v111, v88 row_newbcast:8 row_mask:0xf bank_mask:0xf
	v_fmac_f32_dpp v127, v111, v89 row_newbcast:9 row_mask:0xf bank_mask:0xf
	v_fmac_f32_dpp v126, v111, v90 row_newbcast:10 row_mask:0xf bank_mask:0xf
	v_fmac_f32_dpp v127, v111, v91 row_newbcast:11 row_mask:0xf bank_mask:0xf
	v_fmac_f32_dpp v126, v111, v92 row_newbcast:12 row_mask:0xf bank_mask:0xf
	v_fmac_f32_dpp v127, v111, v93 row_newbcast:13 row_mask:0xf bank_mask:0xf
	v_fmac_f32_dpp v126, v111, v94 row_newbcast:14 row_mask:0xf bank_mask:0xf
	v_fmac_f32_dpp v127, v111, v95 row_newbcast:15 row_mask:0xf bank_mask:0xf
	v_add_f32_e32 v124, v124, v125
	v_add_f32_e32 v126, v126, v127
	v_add_f32_e32 v130, v124, v126
	s_nop 1
	v_permlane32_swap_b32 v131, v130
	s_mov_b32 exec_lo, 0
	v_add_f32_e32 v133, v131, v130
	v_cvt_pk_bf16_f32 v133, v133, v133
	global_store_short v13, v133, s[16:17]
	s_mov_b32 exec_lo, -1
	s_add_u32 s16, s16, s20
	s_addc_u32 s17, s17, s21
	s_waitcnt lgkmcnt(0)
	ds_read_b32 v102, v14 offset:23296
	ds_read_b32 v103, v14 offset:23424
	ds_read_b32 v106, v15 offset:23040
	ds_read_b32 v107, v15 offset:23168
	ds_read_b32 v109, v16 offset:23040
	ds_read_b32 v116, v14 offset:24064
	ds_read_b32 v117, v14 offset:24192
	ds_read_b32 v118, v14 offset:23040
	ds_read_b32 v119, v14 offset:23168
	v_mul_f32_dpp v120, v100, v32 row_newbcast:0 row_mask:0xf bank_mask:0xf
	v_mul_f32_dpp v121, v100, v33 row_newbcast:1 row_mask:0xf bank_mask:0xf
	v_fmac_f32_dpp v120, v100, v34 row_newbcast:2 row_mask:0xf bank_mask:0xf
	v_fmac_f32_dpp v121, v100, v35 row_newbcast:3 row_mask:0xf bank_mask:0xf
	v_fmac_f32_dpp v120, v100, v36 row_newbcast:4 row_mask:0xf bank_mask:0xf
	v_fmac_f32_dpp v121, v100, v37 row_newbcast:5 row_mask:0xf bank_mask:0xf
	v_fmac_f32_dpp v120, v100, v38 row_newbcast:6 row_mask:0xf bank_mask:0xf
	v_fmac_f32_dpp v121, v100, v39 row_newbcast:7 row_mask:0xf bank_mask:0xf
	v_fmac_f32_dpp v120, v100, v40 row_newbcast:8 row_mask:0xf bank_mask:0xf
	v_fmac_f32_dpp v121, v100, v41 row_newbcast:9 row_mask:0xf bank_mask:0xf
	v_fmac_f32_dpp v120, v100, v42 row_newbcast:10 row_mask:0xf bank_mask:0xf
	v_fmac_f32_dpp v121, v100, v43 row_newbcast:11 row_mask:0xf bank_mask:0xf
	v_fmac_f32_dpp v120, v100, v44 row_newbcast:12 row_mask:0xf bank_mask:0xf
	v_fmac_f32_dpp v121, v100, v45 row_newbcast:13 row_mask:0xf bank_mask:0xf
	v_fmac_f32_dpp v120, v100, v46 row_newbcast:14 row_mask:0xf bank_mask:0xf
	v_fmac_f32_dpp v121, v100, v47 row_newbcast:15 row_mask:0xf bank_mask:0xf
	v_mul_f32_dpp v122, v101, v48 row_newbcast:0 row_mask:0xf bank_mask:0xf
	v_mul_f32_dpp v123, v101, v49 row_newbcast:1 row_mask:0xf bank_mask:0xf
	v_fmac_f32_dpp v122, v101, v50 row_newbcast:2 row_mask:0xf bank_mask:0xf
	v_fmac_f32_dpp v123, v101, v51 row_newbcast:3 row_mask:0xf bank_mask:0xf
	v_fmac_f32_dpp v122, v101, v52 row_newbcast:4 row_mask:0xf bank_mask:0xf
	v_fmac_f32_dpp v123, v101, v53 row_newbcast:5 row_mask:0xf bank_mask:0xf
	v_fmac_f32_dpp v122, v101, v54 row_newbcast:6 row_mask:0xf bank_mask:0xf
	v_fmac_f32_dpp v123, v101, v55 row_newbcast:7 row_mask:0xf bank_mask:0xf
	v_fmac_f32_dpp v122, v101, v56 row_newbcast:8 row_mask:0xf bank_mask:0xf
	v_fmac_f32_dpp v123, v101, v57 row_newbcast:9 row_mask:0xf bank_mask:0xf
	v_fmac_f32_dpp v122, v101, v58 row_newbcast:10 row_mask:0xf bank_mask:0xf
	v_fmac_f32_dpp v123, v101, v59 row_newbcast:11 row_mask:0xf bank_mask:0xf
	v_fmac_f32_dpp v122, v101, v60 row_newbcast:12 row_mask:0xf bank_mask:0xf
	v_fmac_f32_dpp v123, v101, v61 row_newbcast:13 row_mask:0xf bank_mask:0xf
	v_fmac_f32_dpp v122, v101, v62 row_newbcast:14 row_mask:0xf bank_mask:0xf
	v_fmac_f32_dpp v123, v101, v63 row_newbcast:15 row_mask:0xf bank_mask:0xf
	v_add_f32_e32 v120, v120, v121
	v_add_f32_e32 v122, v122, v123
	v_add_f32_e32 v128, v120, v122
	s_nop 1
	v_permlane32_swap_b32 v129, v128
	s_mov_b32 exec_lo, 0
	v_add_f32_e64 v108, -v129, -v128
	s_mov_b32 exec_lo, -1
	s_nop 0
	v_mfma_f32_32x32x2_f32 v[64:79], v104, v108, v[32:47]
	v_mul_f32_dpp v124, v112, v32 row_newbcast:0 row_mask:0xf bank_mask:0xf
	v_mul_f32_dpp v125, v112, v33 row_newbcast:1 row_mask:0xf bank_mask:0xf
	v_fmac_f32_dpp v124, v112, v34 row_newbcast:2 row_mask:0xf bank_mask:0xf
	v_fmac_f32_dpp v125, v112, v35 row_newbcast:3 row_mask:0xf bank_mask:0xf
	v_fmac_f32_dpp v124, v112, v36 row_newbcast:4 row_mask:0xf bank_mask:0xf
	v_fmac_f32_dpp v125, v112, v37 row_newbcast:5 row_mask:0xf bank_mask:0xf
	v_fmac_f32_dpp v124, v112, v38 row_newbcast:6 row_mask:0xf bank_mask:0xf
	v_fmac_f32_dpp v125, v112, v39 row_newbcast:7 row_mask:0xf bank_mask:0xf
	v_fmac_f32_dpp v124, v112, v40 row_newbcast:8 row_mask:0xf bank_mask:0xf
	v_fmac_f32_dpp v125, v112, v41 row_newbcast:9 row_mask:0xf bank_mask:0xf
	v_fmac_f32_dpp v124, v112, v42 row_newbcast:10 row_mask:0xf bank_mask:0xf
	v_fmac_f32_dpp v125, v112, v43 row_newbcast:11 row_mask:0xf bank_mask:0xf
	v_fmac_f32_dpp v124, v112, v44 row_newbcast:12 row_mask:0xf bank_mask:0xf
	v_fmac_f32_dpp v125, v112, v45 row_newbcast:13 row_mask:0xf bank_mask:0xf
	v_fmac_f32_dpp v124, v112, v46 row_newbcast:14 row_mask:0xf bank_mask:0xf
	v_fmac_f32_dpp v125, v112, v47 row_newbcast:15 row_mask:0xf bank_mask:0xf
	v_mfma_f32_32x32x2_f32 v[80:95], v105, v108, v[48:63]
	v_mul_f32_dpp v126, v113, v48 row_newbcast:0 row_mask:0xf bank_mask:0xf
	v_mul_f32_dpp v127, v113, v49 row_newbcast:1 row_mask:0xf bank_mask:0xf
	v_fmac_f32_dpp v126, v113, v50 row_newbcast:2 row_mask:0xf bank_mask:0xf
	v_fmac_f32_dpp v127, v113, v51 row_newbcast:3 row_mask:0xf bank_mask:0xf
	v_fmac_f32_dpp v126, v113, v52 row_newbcast:4 row_mask:0xf bank_mask:0xf
	v_fmac_f32_dpp v127, v113, v53 row_newbcast:5 row_mask:0xf bank_mask:0xf
	v_fmac_f32_dpp v126, v113, v54 row_newbcast:6 row_mask:0xf bank_mask:0xf
	v_fmac_f32_dpp v127, v113, v55 row_newbcast:7 row_mask:0xf bank_mask:0xf
	v_fmac_f32_dpp v126, v113, v56 row_newbcast:8 row_mask:0xf bank_mask:0xf
	v_fmac_f32_dpp v127, v113, v57 row_newbcast:9 row_mask:0xf bank_mask:0xf
	v_fmac_f32_dpp v126, v113, v58 row_newbcast:10 row_mask:0xf bank_mask:0xf
	v_fmac_f32_dpp v127, v113, v59 row_newbcast:11 row_mask:0xf bank_mask:0xf
	v_fmac_f32_dpp v126, v113, v60 row_newbcast:12 row_mask:0xf bank_mask:0xf
	v_fmac_f32_dpp v127, v113, v61 row_newbcast:13 row_mask:0xf bank_mask:0xf
	v_fmac_f32_dpp v126, v113, v62 row_newbcast:14 row_mask:0xf bank_mask:0xf
	v_fmac_f32_dpp v127, v113, v63 row_newbcast:15 row_mask:0xf bank_mask:0xf
	v_add_f32_e32 v124, v124, v125
	v_add_f32_e32 v126, v126, v127
	v_add_f32_e32 v130, v124, v126
	s_nop 1
	v_permlane32_swap_b32 v131, v130
	s_mov_b32 exec_lo, 0
	v_add_f32_e32 v133, v131, v130
	v_cvt_pk_bf16_f32 v133, v133, v133
	global_store_short v13, v133, s[16:17]
	s_mov_b32 exec_lo, -1
	s_add_u32 s16, s16, s20
	s_addc_u32 s17, s17, s21
	s_waitcnt lgkmcnt(0)
	v_mul_f32_dpp v120, v102, v64 row_newbcast:0 row_mask:0xf bank_mask:0xf
	v_mul_f32_dpp v121, v102, v65 row_newbcast:1 row_mask:0xf bank_mask:0xf
	v_fmac_f32_dpp v120, v102, v66 row_newbcast:2 row_mask:0xf bank_mask:0xf
	v_fmac_f32_dpp v121, v102, v67 row_newbcast:3 row_mask:0xf bank_mask:0xf
	v_fmac_f32_dpp v120, v102, v68 row_newbcast:4 row_mask:0xf bank_mask:0xf
	v_fmac_f32_dpp v121, v102, v69 row_newbcast:5 row_mask:0xf bank_mask:0xf
	v_fmac_f32_dpp v120, v102, v70 row_newbcast:6 row_mask:0xf bank_mask:0xf
	v_fmac_f32_dpp v121, v102, v71 row_newbcast:7 row_mask:0xf bank_mask:0xf
	v_fmac_f32_dpp v120, v102, v72 row_newbcast:8 row_mask:0xf bank_mask:0xf
	v_fmac_f32_dpp v121, v102, v73 row_newbcast:9 row_mask:0xf bank_mask:0xf
	v_fmac_f32_dpp v120, v102, v74 row_newbcast:10 row_mask:0xf bank_mask:0xf
	v_fmac_f32_dpp v121, v102, v75 row_newbcast:11 row_mask:0xf bank_mask:0xf
	v_fmac_f32_dpp v120, v102, v76 row_newbcast:12 row_mask:0xf bank_mask:0xf
	v_fmac_f32_dpp v121, v102, v77 row_newbcast:13 row_mask:0xf bank_mask:0xf
	v_fmac_f32_dpp v120, v102, v78 row_newbcast:14 row_mask:0xf bank_mask:0xf
	v_fmac_f32_dpp v121, v102, v79 row_newbcast:15 row_mask:0xf bank_mask:0xf
	v_mul_f32_dpp v122, v103, v80 row_newbcast:0 row_mask:0xf bank_mask:0xf
	v_mul_f32_dpp v123, v103, v81 row_newbcast:1 row_mask:0xf bank_mask:0xf
	v_fmac_f32_dpp v122, v103, v82 row_newbcast:2 row_mask:0xf bank_mask:0xf
	v_fmac_f32_dpp v123, v103, v83 row_newbcast:3 row_mask:0xf bank_mask:0xf
	v_fmac_f32_dpp v122, v103, v84 row_newbcast:4 row_mask:0xf bank_mask:0xf
	v_fmac_f32_dpp v123, v103, v85 row_newbcast:5 row_mask:0xf bank_mask:0xf
	v_fmac_f32_dpp v122, v103, v86 row_newbcast:6 row_mask:0xf bank_mask:0xf
	v_fmac_f32_dpp v123, v103, v87 row_newbcast:7 row_mask:0xf bank_mask:0xf
	v_fmac_f32_dpp v122, v103, v88 row_newbcast:8 row_mask:0xf bank_mask:0xf
	v_fmac_f32_dpp v123, v103, v89 row_newbcast:9 row_mask:0xf bank_mask:0xf
	v_fmac_f32_dpp v122, v103, v90 row_newbcast:10 row_mask:0xf bank_mask:0xf
	v_fmac_f32_dpp v123, v103, v91 row_newbcast:11 row_mask:0xf bank_mask:0xf
	v_fmac_f32_dpp v122, v103, v92 row_newbcast:12 row_mask:0xf bank_mask:0xf
	v_fmac_f32_dpp v123, v103, v93 row_newbcast:13 row_mask:0xf bank_mask:0xf
	v_fmac_f32_dpp v122, v103, v94 row_newbcast:14 row_mask:0xf bank_mask:0xf
	v_fmac_f32_dpp v123, v103, v95 row_newbcast:15 row_mask:0xf bank_mask:0xf
	v_add_f32_e32 v120, v120, v121
	v_add_f32_e32 v122, v122, v123
	v_add_f32_e32 v128, v120, v122
	s_nop 1
	v_permlane32_swap_b32 v129, v128
	s_mov_b32 exec_lo, 0
	v_add_f32_e64 v109, -v129, -v128
	s_mov_b32 exec_lo, -1
	s_nop 0
	v_mfma_f32_32x32x2_f32 v[32:47], v106, v109, v[64:79]
	v_mul_f32_dpp v124, v114, v64 row_newbcast:0 row_mask:0xf bank_mask:0xf
	v_mul_f32_dpp v125, v114, v65 row_newbcast:1 row_mask:0xf bank_mask:0xf
	v_fmac_f32_dpp v124, v114, v66 row_newbcast:2 row_mask:0xf bank_mask:0xf
	v_fmac_f32_dpp v125, v114, v67 row_newbcast:3 row_mask:0xf bank_mask:0xf
	v_fmac_f32_dpp v124, v114, v68 row_newbcast:4 row_mask:0xf bank_mask:0xf
	v_fmac_f32_dpp v125, v114, v69 row_newbcast:5 row_mask:0xf bank_mask:0xf
	v_fmac_f32_dpp v124, v114, v70 row_newbcast:6 row_mask:0xf bank_mask:0xf
	v_fmac_f32_dpp v125, v114, v71 row_newbcast:7 row_mask:0xf bank_mask:0xf
	v_fmac_f32_dpp v124, v114, v72 row_newbcast:8 row_mask:0xf bank_mask:0xf
	v_fmac_f32_dpp v125, v114, v73 row_newbcast:9 row_mask:0xf bank_mask:0xf
	v_fmac_f32_dpp v124, v114, v74 row_newbcast:10 row_mask:0xf bank_mask:0xf
	v_fmac_f32_dpp v125, v114, v75 row_newbcast:11 row_mask:0xf bank_mask:0xf
	v_fmac_f32_dpp v124, v114, v76 row_newbcast:12 row_mask:0xf bank_mask:0xf
	v_fmac_f32_dpp v125, v114, v77 row_newbcast:13 row_mask:0xf bank_mask:0xf
	v_fmac_f32_dpp v124, v114, v78 row_newbcast:14 row_mask:0xf bank_mask:0xf
	v_fmac_f32_dpp v125, v114, v79 row_newbcast:15 row_mask:0xf bank_mask:0xf
	v_mfma_f32_32x32x2_f32 v[48:63], v107, v109, v[80:95]
	v_mul_f32_dpp v126, v115, v80 row_newbcast:0 row_mask:0xf bank_mask:0xf
	v_mul_f32_dpp v127, v115, v81 row_newbcast:1 row_mask:0xf bank_mask:0xf
	v_fmac_f32_dpp v126, v115, v82 row_newbcast:2 row_mask:0xf bank_mask:0xf
	v_fmac_f32_dpp v127, v115, v83 row_newbcast:3 row_mask:0xf bank_mask:0xf
	v_fmac_f32_dpp v126, v115, v84 row_newbcast:4 row_mask:0xf bank_mask:0xf
	v_fmac_f32_dpp v127, v115, v85 row_newbcast:5 row_mask:0xf bank_mask:0xf
	v_fmac_f32_dpp v126, v115, v86 row_newbcast:6 row_mask:0xf bank_mask:0xf
	v_fmac_f32_dpp v127, v115, v87 row_newbcast:7 row_mask:0xf bank_mask:0xf
	v_fmac_f32_dpp v126, v115, v88 row_newbcast:8 row_mask:0xf bank_mask:0xf
	v_fmac_f32_dpp v127, v115, v89 row_newbcast:9 row_mask:0xf bank_mask:0xf
	v_fmac_f32_dpp v126, v115, v90 row_newbcast:10 row_mask:0xf bank_mask:0xf
	v_fmac_f32_dpp v127, v115, v91 row_newbcast:11 row_mask:0xf bank_mask:0xf
	v_fmac_f32_dpp v126, v115, v92 row_newbcast:12 row_mask:0xf bank_mask:0xf
	v_fmac_f32_dpp v127, v115, v93 row_newbcast:13 row_mask:0xf bank_mask:0xf
	v_fmac_f32_dpp v126, v115, v94 row_newbcast:14 row_mask:0xf bank_mask:0xf
	v_fmac_f32_dpp v127, v115, v95 row_newbcast:15 row_mask:0xf bank_mask:0xf
	v_add_f32_e32 v124, v124, v125
	v_add_f32_e32 v126, v126, v127
	v_add_f32_e32 v130, v124, v126
	s_nop 1
	v_permlane32_swap_b32 v131, v130
	s_mov_b32 exec_lo, 0
	v_add_f32_e32 v133, v131, v130
	v_cvt_pk_bf16_f32 v133, v133, v133
	global_store_short v13, v133, s[16:17]
	s_mov_b32 exec_lo, -1
	s_add_u32 s16, s16, s20
	s_addc_u32 s17, s17, s21
	v_mul_f32_dpp v124, v116, v32 row_newbcast:0 row_mask:0xf bank_mask:0xf
	v_mul_f32_dpp v125, v116, v33 row_newbcast:1 row_mask:0xf bank_mask:0xf
	v_fmac_f32_dpp v124, v116, v34 row_newbcast:2 row_mask:0xf bank_mask:0xf
	v_fmac_f32_dpp v125, v116, v35 row_newbcast:3 row_mask:0xf bank_mask:0xf
	v_fmac_f32_dpp v124, v116, v36 row_newbcast:4 row_mask:0xf bank_mask:0xf
	v_fmac_f32_dpp v125, v116, v37 row_newbcast:5 row_mask:0xf bank_mask:0xf
	v_fmac_f32_dpp v124, v116, v38 row_newbcast:6 row_mask:0xf bank_mask:0xf
	v_fmac_f32_dpp v125, v116, v39 row_newbcast:7 row_mask:0xf bank_mask:0xf
	v_fmac_f32_dpp v124, v116, v40 row_newbcast:8 row_mask:0xf bank_mask:0xf
	v_fmac_f32_dpp v125, v116, v41 row_newbcast:9 row_mask:0xf bank_mask:0xf
	v_fmac_f32_dpp v124, v116, v42 row_newbcast:10 row_mask:0xf bank_mask:0xf
	v_fmac_f32_dpp v125, v116, v43 row_newbcast:11 row_mask:0xf bank_mask:0xf
; __device__ void scan_chain(PRef p, int l, int chain, ScanSm* sm) {
;     ...
; #pragma unroll 1
;     for (int c = 0; c < 144; c++) {
;       __syncthreads();
;       const ScanRec* rc0 = &sm->rec[c & 1][0];
;       LDSET(A, rc0)
; #pragma unroll 1
;       for (int i2 = 0; i2 < 8; i2++) {
;         const ScanRec* rcA = rc0 + 2 * i2;
;         const ScanRec* rcC = (i2 < 7) ? rcA + 2 : rcA + 1;
;         LDSET(B, rcA + 1)
;         SCAN_STEP(A, c * 16 + 2 * i2)
;         LDSET(A, rcC)
;         SCAN_STEP(B, c * 16 + 2 * i2 + 1)
;       }
;     }
	v_fmac_f32_dpp v124, v116, v44 row_newbcast:12 row_mask:0xf bank_mask:0xf
	v_fmac_f32_dpp v125, v116, v45 row_newbcast:13 row_mask:0xf bank_mask:0xf
	v_fmac_f32_dpp v124, v116, v46 row_newbcast:14 row_mask:0xf bank_mask:0xf
	v_fmac_f32_dpp v125, v116, v47 row_newbcast:15 row_mask:0xf bank_mask:0xf
	v_mul_f32_dpp v126, v117, v48 row_newbcast:0 row_mask:0xf bank_mask:0xf
	v_mul_f32_dpp v127, v117, v49 row_newbcast:1 row_mask:0xf bank_mask:0xf
	v_fmac_f32_dpp v126, v117, v50 row_newbcast:2 row_mask:0xf bank_mask:0xf
	v_fmac_f32_dpp v127, v117, v51 row_newbcast:3 row_mask:0xf bank_mask:0xf
	v_fmac_f32_dpp v126, v117, v52 row_newbcast:4 row_mask:0xf bank_mask:0xf
	v_fmac_f32_dpp v127, v117, v53 row_newbcast:5 row_mask:0xf bank_mask:0xf
	v_fmac_f32_dpp v126, v117, v54 row_newbcast:6 row_mask:0xf bank_mask:0xf
	v_fmac_f32_dpp v127, v117, v55 row_newbcast:7 row_mask:0xf bank_mask:0xf
	v_fmac_f32_dpp v126, v117, v56 row_newbcast:8 row_mask:0xf bank_mask:0xf
	v_fmac_f32_dpp v127, v117, v57 row_newbcast:9 row_mask:0xf bank_mask:0xf
	v_fmac_f32_dpp v126, v117, v58 row_newbcast:10 row_mask:0xf bank_mask:0xf
	v_fmac_f32_dpp v127, v117, v59 row_newbcast:11 row_mask:0xf bank_mask:0xf
	v_fmac_f32_dpp v126, v117, v60 row_newbcast:12 row_mask:0xf bank_mask:0xf
	v_fmac_f32_dpp v127, v117, v61 row_newbcast:13 row_mask:0xf bank_mask:0xf
	v_fmac_f32_dpp v126, v117, v62 row_newbcast:14 row_mask:0xf bank_mask:0xf
	v_fmac_f32_dpp v127, v117, v63 row_newbcast:15 row_mask:0xf bank_mask:0xf
	v_add_f32_e32 v124, v124, v125
	v_add_f32_e32 v126, v126, v127
	v_add_f32_e32 v130, v124, v126
	s_nop 1
	v_permlane32_swap_b32 v131, v130
	s_mov_b32 exec_lo, 0
	v_add_f32_e32 v133, v131, v130
	v_cvt_pk_bf16_f32 v133, v133, v133
	global_store_short v13, v133, s[16:17]
	s_mov_b32 exec_lo, -1
	s_add_u32 s16, s16, s20
	s_addc_u32 s17, s17, s21
	v_mul_f32_dpp v32, v118, v32 row_newbcast:0 row_mask:0xf bank_mask:0xf
	v_mul_f32_dpp v33, v118, v33 row_newbcast:1 row_mask:0xf bank_mask:0xf
	v_mul_f32_dpp v34, v118, v34 row_newbcast:2 row_mask:0xf bank_mask:0xf
	v_mul_f32_dpp v35, v118, v35 row_newbcast:3 row_mask:0xf bank_mask:0xf
	v_mul_f32_dpp v36, v118, v36 row_newbcast:4 row_mask:0xf bank_mask:0xf
	v_mul_f32_dpp v37, v118, v37 row_newbcast:5 row_mask:0xf bank_mask:0xf
	v_mul_f32_dpp v38, v118, v38 row_newbcast:6 row_mask:0xf bank_mask:0xf
	v_mul_f32_dpp v39, v118, v39 row_newbcast:7 row_mask:0xf bank_mask:0xf
	v_mul_f32_dpp v40, v118, v40 row_newbcast:8 row_mask:0xf bank_mask:0xf
	v_mul_f32_dpp v41, v118, v41 row_newbcast:9 row_mask:0xf bank_mask:0xf
	v_mul_f32_dpp v42, v118, v42 row_newbcast:10 row_mask:0xf bank_mask:0xf
	v_mul_f32_dpp v43, v118, v43 row_newbcast:11 row_mask:0xf bank_mask:0xf
	v_mul_f32_dpp v44, v118, v44 row_newbcast:12 row_mask:0xf bank_mask:0xf
	v_mul_f32_dpp v45, v118, v45 row_newbcast:13 row_mask:0xf bank_mask:0xf
	v_mul_f32_dpp v46, v118, v46 row_newbcast:14 row_mask:0xf bank_mask:0xf
	v_mul_f32_dpp v47, v118, v47 row_newbcast:15 row_mask:0xf bank_mask:0xf
	v_mul_f32_dpp v48, v119, v48 row_newbcast:0 row_mask:0xf bank_mask:0xf
	v_mul_f32_dpp v49, v119, v49 row_newbcast:1 row_mask:0xf bank_mask:0xf
	v_mul_f32_dpp v50, v119, v50 row_newbcast:2 row_mask:0xf bank_mask:0xf
	v_mul_f32_dpp v51, v119, v51 row_newbcast:3 row_mask:0xf bank_mask:0xf
	v_mul_f32_dpp v52, v119, v52 row_newbcast:4 row_mask:0xf bank_mask:0xf
	v_mul_f32_dpp v53, v119, v53 row_newbcast:5 row_mask:0xf bank_mask:0xf
	v_mul_f32_dpp v54, v119, v54 row_newbcast:6 row_mask:0xf bank_mask:0xf
	v_mul_f32_dpp v55, v119, v55 row_newbcast:7 row_mask:0xf bank_mask:0xf
	v_mul_f32_dpp v56, v119, v56 row_newbcast:8 row_mask:0xf bank_mask:0xf
	v_mul_f32_dpp v57, v119, v57 row_newbcast:9 row_mask:0xf bank_mask:0xf
	v_mul_f32_dpp v58, v119, v58 row_newbcast:10 row_mask:0xf bank_mask:0xf
	v_mul_f32_dpp v59, v119, v59 row_newbcast:11 row_mask:0xf bank_mask:0xf
	v_mul_f32_dpp v60, v119, v60 row_newbcast:12 row_mask:0xf bank_mask:0xf
	v_mul_f32_dpp v61, v119, v61 row_newbcast:13 row_mask:0xf bank_mask:0xf
	v_mul_f32_dpp v62, v119, v62 row_newbcast:14 row_mask:0xf bank_mask:0xf
	v_mul_f32_dpp v63, v119, v63 row_newbcast:15 row_mask:0xf bank_mask:0xf
	s_add_i32 s15, s15, 1
	s_cmpk_lg_i32 s15, 0x90
	s_cbranch_scc1 .Lscan_chunk
	s_branch .LBB0_564
